# gemm256 K-loops: LDS-DMA with 32-bit lane offsets + SGPR bases (saddr form) instead of 64-bit lane addresses
# baseline (speedup 1.0000x reference)
; #define GLDS_STAGE(st, kt_) do { \
;         _Pragma("unroll") for (int i_ = 0; i_ < FI; ++i_) { \
;             glds16(ap + (size_t)(32 * i_) * lda + (kt_) * 64, l3a + (st) + tid * 16 + i_ * 4096); \
;             glds16(bp + (size_t)(32 * i_) * ldb + (kt_) * 64, l3a + (st) + OPB + tid * 16 + i_ * 4096); } } while (0)
; #define GLDS_STAGE(st, kt_) do { \
;         _Pragma("unroll") for (int i_ = 0; i_ < 4; ++i_) { \
;             glds16(ap + (size_t)(64 * i_) * lda + (kt_) * 64, l3a + (st) + tid * 16 + i_ * 8192); \
;             glds16(bp + (size_t)(64 * i_) * ldb + (kt_) * 64, l3a + (st) + 32768 + tid * 16 + i_ * 8192); } } while (0)
; template <class Epi>
; DEV void gemm256_tile(const bf16_t* __restrict__ A, int lda, const bf16_t* __restrict__ Bt, int ldb, int K, unsigned char* lds, const Epi& epi) {
;     ...
;     GLDS_STAGE(0, 0);
;     const int aoff = (wr * 128 + fr) * 128, boff = 32768 + (wc * 64 + fr) * 128, sw = fr & 7;
;     for (int kt = 0; kt < nk; ++kt) {
;         const int cur = (kt & 1) * 65536;
;         asm volatile("s_waitcnt vmcnt(0)" ::: "memory");
;         __syncthreads();
;         if (kt + 1 < nk) GLDS_STAGE(cur ^ 65536, kt + 1);
; #pragma unroll
;         for (int kh = 0; kh < 2; ++kh) {
;             bf16x8 bfr[4];
;             const int ch = ((kh * 4 + fq) ^ sw) << 4;
; #pragma unroll
;             for (int i = 0; i < 4; ++i) bfr[i] = *(const bf16x8*)(lds + cur + boff + i * 2048 + ch);
; #pragma unroll
;             for (int mh = 0; mh < 2; ++mh) {
;                 bf16x8 af[4];
; #pragma unroll
;                 for (int i = 0; i < 4; ++i) af[i] = *(const bf16x8*)(lds + cur + aoff + (mh * 4 + i) * 2048 + ch);
.LBB0_174:
	s_and_b32 s48, s21, 0x10000
	s_xor_b32 s49, s48, 0x10000
	v_add_u32_e32 v216, s49, v142
	v_add_u32_e32 v217, s49, v156
	s_waitcnt vmcnt(0) lgkmcnt(0)
	s_barrier
	v_readfirstlane_b32 s50, v144
	v_readfirstlane_b32 s51, v145
	v_readfirstlane_b32 s58, v146
	v_readfirstlane_b32 s59, v147
	v_or_b32_e32 v248, s48, v175
	v_add_u32_e32 v249, s48, v157
	v_add_u32_e32 v244, v248, v174
	v_add_u32_e32 v245, v249, v174
	ds_read_b128 v[176:179], v244 offset:32768
	ds_read_b128 v[180:183], v244 offset:34816
	ds_read_b128 v[184:187], v244 offset:36864
	ds_read_b128 v[188:191], v244 offset:38912
	ds_read_b128 v[228:231], v245
	ds_read_b128 v[232:235], v245 offset:2048
	ds_read_b128 v[236:239], v245 offset:4096
	ds_read_b128 v[240:243], v245 offset:6144
	v_readfirstlane_b32 s40, v216
	v_readfirstlane_b32 s44, v217
	v_subrev_u32_e32 v218, s50, v144
	v_subrev_u32_e32 v219, s58, v146
	v_add_u32_e32 v246, v248, v155
	v_add_u32_e32 v247, v249, v155
	s_mov_b32 m0, s40
	s_add_u32 s52, s50, s4
	s_addc_u32 s53, s51, s5
	global_load_lds_dwordx4 v218, s[50:51]
	s_mov_b32 m0, s44
	s_add_u32 s60, s58, s4
	s_addc_u32 s61, s59, s5
	global_load_lds_dwordx4 v219, s[58:59]
	s_add_i32 s41, s40, 0x2000
	s_add_i32 s45, s44, 0x2000
	s_add_i32 s42, s40, 0x4000
	s_add_i32 s46, s44, 0x4000
	s_add_i32 s43, s40, 0x6000
	s_add_i32 s47, s44, 0x6000
	s_add_i32 s21, s21, 0x10000
	s_waitcnt lgkmcnt(3)
	v_mfma_f32_16x16x32_bf16 v[126:129], v[176:179], v[228:231], v[126:129]
	s_add_u32 s54, s50, s6
	s_addc_u32 s55, s51, s7
	v_mfma_f32_16x16x32_bf16 v[122:125], v[180:183], v[228:231], v[122:125]
	s_add_u32 s62, s58, s6
	s_addc_u32 s63, s59, s7
	v_mfma_f32_16x16x32_bf16 v[118:121], v[184:187], v[228:231], v[118:121]
	s_add_u32 s56, s50, s8
	s_addc_u32 s57, s51, s9
	v_mfma_f32_16x16x32_bf16 v[114:117], v[188:191], v[228:231], v[114:117]
	s_add_u32 s64, s58, s8
	s_addc_u32 s65, s59, s9
	s_waitcnt lgkmcnt(2)
	v_mfma_f32_16x16x32_bf16 v[110:113], v[176:179], v[232:235], v[110:113]
	v_mfma_f32_16x16x32_bf16 v[106:109], v[180:183], v[232:235], v[106:109]
	v_mfma_f32_16x16x32_bf16 v[102:105], v[184:187], v[232:235], v[102:105]
	v_mfma_f32_16x16x32_bf16 v[98:101], v[188:191], v[232:235], v[98:101]
	s_waitcnt lgkmcnt(1)
	v_mfma_f32_16x16x32_bf16 v[94:97], v[176:179], v[236:239], v[94:97]
	ds_read_b128 v[228:231], v245 offset:8192
	v_mfma_f32_16x16x32_bf16 v[90:93], v[180:183], v[236:239], v[90:93]
	ds_read_b128 v[232:235], v245 offset:10240
	v_mfma_f32_16x16x32_bf16 v[86:89], v[184:187], v[236:239], v[86:89]
	s_mov_b32 m0, s41
	v_mfma_f32_16x16x32_bf16 v[82:85], v[188:191], v[236:239], v[82:85]
	global_load_lds_dwordx4 v218, s[52:53]
	s_waitcnt lgkmcnt(2)
	v_mfma_f32_16x16x32_bf16 v[78:81], v[176:179], v[240:243], v[78:81]
	s_mov_b32 m0, s45
	v_mfma_f32_16x16x32_bf16 v[74:77], v[180:183], v[240:243], v[74:77]
	global_load_lds_dwordx4 v219, s[60:61]
	v_mfma_f32_16x16x32_bf16 v[70:73], v[184:187], v[240:243], v[70:73]
	v_mfma_f32_16x16x32_bf16 v[66:69], v[188:191], v[240:243], v[66:69]
	s_waitcnt lgkmcnt(1)
	v_mfma_f32_16x16x32_bf16 v[62:65], v[176:179], v[228:231], v[62:65]
	ds_read_b128 v[236:239], v245 offset:12288
	v_mfma_f32_16x16x32_bf16 v[58:61], v[180:183], v[228:231], v[58:61]
	ds_read_b128 v[240:243], v245 offset:14336
	v_mfma_f32_16x16x32_bf16 v[54:57], v[184:187], v[228:231], v[54:57]
	s_mov_b32 m0, s42
	v_mfma_f32_16x16x32_bf16 v[50:53], v[188:191], v[228:231], v[50:53]
	global_load_lds_dwordx4 v218, s[54:55]
	s_waitcnt lgkmcnt(2)
	v_mfma_f32_16x16x32_bf16 v[46:49], v[176:179], v[232:235], v[46:49]
	s_mov_b32 m0, s46
	v_mfma_f32_16x16x32_bf16 v[42:45], v[180:183], v[232:235], v[42:45]
	global_load_lds_dwordx4 v219, s[62:63]
	v_mfma_f32_16x16x32_bf16 v[34:37], v[184:187], v[232:235], v[34:37]
	v_mfma_f32_16x16x32_bf16 v[30:33], v[188:191], v[232:235], v[30:33]
	s_waitcnt lgkmcnt(1)
	v_mfma_f32_16x16x32_bf16 v[26:29], v[176:179], v[236:239], v[26:29]
	ds_read_b128 v[192:195], v246 offset:32768
	v_mfma_f32_16x16x32_bf16 v[22:25], v[180:183], v[236:239], v[22:25]
	ds_read_b128 v[196:199], v246 offset:34816
	v_mfma_f32_16x16x32_bf16 v[18:21], v[184:187], v[236:239], v[18:21]
	ds_read_b128 v[220:223], v246 offset:36864
	v_mfma_f32_16x16x32_bf16 v[14:17], v[188:191], v[236:239], v[14:17]
	ds_read_b128 v[224:227], v246 offset:38912
	s_waitcnt lgkmcnt(4)
	v_mfma_f32_16x16x32_bf16 v[10:13], v[176:179], v[240:243], v[10:13]
	ds_read_b128 v[228:231], v247
	v_mfma_f32_16x16x32_bf16 v[6:9], v[180:183], v[240:243], v[6:9]
	ds_read_b128 v[232:235], v247 offset:2048
	v_mfma_f32_16x16x32_bf16 v[2:5], v[184:187], v[240:243], v[2:5]
	s_mov_b32 m0, s43
	v_mfma_f32_16x16x32_bf16 v[38:41], v[188:191], v[240:243], v[38:41]
	global_load_lds_dwordx4 v218, s[56:57]
	s_mov_b32 m0, s47
	v_lshl_add_u64 v[144:145], v[144:145], 0, s[10:11]
	global_load_lds_dwordx4 v219, s[64:65]
	v_lshl_add_u64 v[146:147], v[146:147], 0, s[10:11]
	s_waitcnt lgkmcnt(1)
	v_mfma_f32_16x16x32_bf16 v[126:129], v[192:195], v[228:231], v[126:129]
	ds_read_b128 v[236:239], v247 offset:4096
	v_mfma_f32_16x16x32_bf16 v[122:125], v[196:199], v[228:231], v[122:125]
	ds_read_b128 v[240:243], v247 offset:6144
	v_mfma_f32_16x16x32_bf16 v[118:121], v[220:223], v[228:231], v[118:121]
	v_mfma_f32_16x16x32_bf16 v[114:117], v[224:227], v[228:231], v[114:117]
	s_waitcnt lgkmcnt(2)
	v_mfma_f32_16x16x32_bf16 v[110:113], v[192:195], v[232:235], v[110:113]
	v_mfma_f32_16x16x32_bf16 v[106:109], v[196:199], v[232:235], v[106:109]
	v_mfma_f32_16x16x32_bf16 v[102:105], v[220:223], v[232:235], v[102:105]
	v_mfma_f32_16x16x32_bf16 v[98:101], v[224:227], v[232:235], v[98:101]
	s_waitcnt lgkmcnt(1)
; DEV unsigned cvt_pk_bf16(float lo, float hi) { const f32x2_t v = {lo, hi}; const bf16x2_t b = __builtin_convertvector(v, bf16x2_t); return __builtin_bit_cast(unsigned, b); }
; #define GLDS_STAGE(st, kt_) do { \
;         _Pragma("unroll") for (int i_ = 0; i_ < FI; ++i_) { \
;             glds16(ap + (size_t)(32 * i_) * lda + (kt_) * 64, l3a + (st) + tid * 16 + i_ * 4096); \
;             glds16(bp + (size_t)(32 * i_) * ldb + (kt_) * 64, l3a + (st) + OPB + tid * 16 + i_ * 4096); } } while (0)
; template <class Epi>
; DEV void gemm256_tile(const bf16_t* __restrict__ A, int lda, const bf16_t* __restrict__ Bt, int ldb, int K, unsigned char* lds, const Epi& epi) {
;     ...
;     for (int kt = 0; kt < nk; ++kt) {
;         const int cur = (kt & 1) * 65536;
;         asm volatile("s_waitcnt vmcnt(0)" ::: "memory");
;         __syncthreads();
;         if (kt + 1 < nk) GLDS_STAGE(cur ^ 65536, kt + 1);
; #pragma unroll
;         for (int kh = 0; kh < 2; ++kh) {
;             bf16x8 bfr[4];
;             const int ch = ((kh * 4 + fq) ^ sw) << 4;
; #pragma unroll
;             for (int i = 0; i < 4; ++i) bfr[i] = *(const bf16x8*)(lds + cur + boff + i * 2048 + ch);
; #pragma unroll
;             for (int mh = 0; mh < 2; ++mh) {
;                 bf16x8 af[4];
; #pragma unroll
;                 for (int i = 0; i < 4; ++i) af[i] = *(const bf16x8*)(lds + cur + aoff + (mh * 4 + i) * 2048 + ch);
; #pragma unroll
;                 for (int mi = 0; mi < 4; ++mi)
; #pragma unroll
;                     for (int ni = 0; ni < 4; ++ni) acc[mh * 4 + mi][ni] = __builtin_amdgcn_mfma_f32_16x16x32_bf16(bfr[ni], af[mi], acc[mh * 4 + mi][ni], 0, 0, 0);
;             }
;         }
;     }
;     ...
;     __syncthreads();
;     if constexpr (Epi::STAGE) {
; #pragma unroll
;         for (int mi = 0; mi < 8; ++mi)
; #pragma unroll
;             for (int ni = 0; ni < 4; ++ni) {
;                 const int row = wr * 128 + mi * 16 + fr, col = wc * 64 + ni * 16 + fq * 4;
;                 const f32x4 v = epi.xform(row, col, acc[mi][ni]);
;                 uint2 w; w.x = cvt_pk_bf16(v[0], v[1]); w.y = cvt_pk_bf16(v[2], v[3]);
;                 *(uint2*)(lds + row * 512 + ((((col >> 3) ^ (row & 31)) << 4) | (((col >> 2) & 1) << 3))) = w;
	v_mfma_f32_16x16x32_bf16 v[94:97], v[192:195], v[236:239], v[94:97]
	ds_read_b128 v[228:231], v247 offset:8192
	v_mfma_f32_16x16x32_bf16 v[90:93], v[196:199], v[236:239], v[90:93]
	ds_read_b128 v[232:235], v247 offset:10240
	v_mfma_f32_16x16x32_bf16 v[86:89], v[220:223], v[236:239], v[86:89]
	v_mfma_f32_16x16x32_bf16 v[82:85], v[224:227], v[236:239], v[82:85]
	s_waitcnt lgkmcnt(2)
	v_mfma_f32_16x16x32_bf16 v[78:81], v[192:195], v[240:243], v[78:81]
	v_mfma_f32_16x16x32_bf16 v[74:77], v[196:199], v[240:243], v[74:77]
	v_mfma_f32_16x16x32_bf16 v[70:73], v[220:223], v[240:243], v[70:73]
	v_mfma_f32_16x16x32_bf16 v[66:69], v[224:227], v[240:243], v[66:69]
	s_waitcnt lgkmcnt(1)
	v_mfma_f32_16x16x32_bf16 v[62:65], v[192:195], v[228:231], v[62:65]
	ds_read_b128 v[236:239], v247 offset:12288
	v_mfma_f32_16x16x32_bf16 v[58:61], v[196:199], v[228:231], v[58:61]
	ds_read_b128 v[240:243], v247 offset:14336
	v_mfma_f32_16x16x32_bf16 v[54:57], v[220:223], v[228:231], v[54:57]
	v_mfma_f32_16x16x32_bf16 v[50:53], v[224:227], v[228:231], v[50:53]
	s_waitcnt lgkmcnt(2)
	v_mfma_f32_16x16x32_bf16 v[46:49], v[192:195], v[232:235], v[46:49]
	v_mfma_f32_16x16x32_bf16 v[42:45], v[196:199], v[232:235], v[42:45]
	v_mfma_f32_16x16x32_bf16 v[34:37], v[220:223], v[232:235], v[34:37]
	v_mfma_f32_16x16x32_bf16 v[30:33], v[224:227], v[232:235], v[30:33]
	s_waitcnt lgkmcnt(1)
	v_mfma_f32_16x16x32_bf16 v[26:29], v[192:195], v[236:239], v[26:29]
	v_mfma_f32_16x16x32_bf16 v[22:25], v[196:199], v[236:239], v[22:25]
	v_mfma_f32_16x16x32_bf16 v[18:21], v[220:223], v[236:239], v[18:21]
	v_mfma_f32_16x16x32_bf16 v[14:17], v[224:227], v[236:239], v[14:17]
	s_waitcnt lgkmcnt(0)
	v_mfma_f32_16x16x32_bf16 v[10:13], v[192:195], v[240:243], v[10:13]
	v_mfma_f32_16x16x32_bf16 v[6:9], v[196:199], v[240:243], v[6:9]
	v_mfma_f32_16x16x32_bf16 v[2:5], v[220:223], v[240:243], v[2:5]
	v_mfma_f32_16x16x32_bf16 v[38:41], v[224:227], v[240:243], v[38:41]
	s_cmp_eq_u32 s21, 0x1f0000
	s_cbranch_scc0 .LBB0_174
	v_or_b32_e32 v156, 0x18000, v175
	v_add_u32_e32 v157, 0x10000, v157
	v_add_u32_e32 v186, v156, v174
	v_add_u32_e32 v194, v157, v174
	s_waitcnt vmcnt(0)
	s_barrier
	ds_read_b128 v[144:147], v186
	ds_read_b128 v[178:181], v186 offset:2048
	ds_read_b128 v[174:177], v194
	ds_read_b128 v[182:185], v186 offset:4096
	ds_read_b128 v[186:189], v186 offset:6144
	s_waitcnt lgkmcnt(2)
	v_mfma_f32_16x16x32_bf16 v[126:129], v[144:147], v[174:177], v[126:129]
	s_sext_i32_i16 s20, s20
	s_lshl_b32 s20, s20, 8
	s_ashr_i32 s21, s20, 31
	v_mfma_f32_16x16x32_bf16 v[122:125], v[178:181], v[174:177], v[122:125]
	s_waitcnt lgkmcnt(1)
	v_mfma_f32_16x16x32_bf16 v[118:121], v[182:185], v[174:177], v[118:121]
	s_waitcnt lgkmcnt(0)
	v_mfma_f32_16x16x32_bf16 v[114:117], v[186:189], v[174:177], v[114:117]
	ds_read_b128 v[174:177], v194 offset:2048
	s_waitcnt lgkmcnt(0)
	v_mfma_f32_16x16x32_bf16 v[110:113], v[144:147], v[174:177], v[110:113]
	v_mfma_f32_16x16x32_bf16 v[106:109], v[178:181], v[174:177], v[106:109]
	v_mfma_f32_16x16x32_bf16 v[102:105], v[182:185], v[174:177], v[102:105]
	v_mfma_f32_16x16x32_bf16 v[98:101], v[186:189], v[174:177], v[98:101]
	ds_read_b128 v[174:177], v194 offset:4096
	s_waitcnt lgkmcnt(0)
	v_mfma_f32_16x16x32_bf16 v[94:97], v[144:147], v[174:177], v[94:97]
	v_mfma_f32_16x16x32_bf16 v[90:93], v[178:181], v[174:177], v[90:93]
	v_mfma_f32_16x16x32_bf16 v[86:89], v[182:185], v[174:177], v[86:89]
	v_mfma_f32_16x16x32_bf16 v[82:85], v[186:189], v[174:177], v[82:85]
	ds_read_b128 v[174:177], v194 offset:6144
	s_waitcnt lgkmcnt(0)
	v_mfma_f32_16x16x32_bf16 v[78:81], v[144:147], v[174:177], v[78:81]
	v_mfma_f32_16x16x32_bf16 v[74:77], v[178:181], v[174:177], v[74:77]
	v_mfma_f32_16x16x32_bf16 v[70:73], v[182:185], v[174:177], v[70:73]
	v_mfma_f32_16x16x32_bf16 v[66:69], v[186:189], v[174:177], v[66:69]
	ds_read_b128 v[174:177], v194 offset:8192
	ds_read_b128 v[190:193], v194 offset:10240
	s_waitcnt lgkmcnt(1)
	v_mfma_f32_16x16x32_bf16 v[62:65], v[144:147], v[174:177], v[62:65]
	v_mfma_f32_16x16x32_bf16 v[58:61], v[178:181], v[174:177], v[58:61]
	v_mfma_f32_16x16x32_bf16 v[54:57], v[182:185], v[174:177], v[54:57]
	v_mfma_f32_16x16x32_bf16 v[50:53], v[186:189], v[174:177], v[50:53]
	ds_read_b128 v[174:177], v194 offset:12288
	s_waitcnt lgkmcnt(1)
	v_mfma_f32_16x16x32_bf16 v[46:49], v[144:147], v[190:193], v[46:49]
	v_mfma_f32_16x16x32_bf16 v[42:45], v[178:181], v[190:193], v[42:45]
	v_mfma_f32_16x16x32_bf16 v[34:37], v[182:185], v[190:193], v[34:37]
	v_mfma_f32_16x16x32_bf16 v[30:33], v[186:189], v[190:193], v[30:33]
	ds_read_b128 v[190:193], v194 offset:14336
	s_waitcnt lgkmcnt(1)
	v_mfma_f32_16x16x32_bf16 v[194:197], v[144:147], v[174:177], v[26:29]
	s_nop 2
	v_add_u32_e32 v29, v156, v155
	ds_read_b128 v[198:201], v29
	ds_read_b128 v[202:205], v29 offset:2048
	ds_read_b128 v[206:209], v29 offset:4096
	ds_read_b128 v[210:213], v29 offset:6144
	v_add_u32_e32 v29, v157, v155
	v_mfma_f32_16x16x32_bf16 v[22:25], v[178:181], v[174:177], v[22:25]
	v_and_b32_e32 v28, 0xc0, v150
	v_lshl_or_b32 v153, v153, 2, v28
	v_lshlrev_b32_e32 v28, 3, v152
	v_mfma_f32_16x16x32_bf16 v[18:21], v[182:185], v[174:177], v[18:21]
	v_mad_i64_i32 v[26:27], s[22:23], s19, v149, v[172:173]
	v_lshl_add_u64 v[26:27], s[20:21], 1, v[26:27]
	v_mfma_f32_16x16x32_bf16 v[14:17], v[186:189], v[174:177], v[14:17]
	ds_read_b128 v[174:177], v29
	ds_read_b128 v[214:217], v29 offset:2048
	ds_read_b128 v[218:221], v29 offset:4096
	ds_read_b128 v[222:225], v29 offset:6144
	s_mov_b32 s19, 0
	s_waitcnt lgkmcnt(3)
	v_mfma_f32_16x16x32_bf16 v[126:129], v[198:201], v[174:177], v[126:129]
	v_mfma_f32_16x16x32_bf16 v[122:125], v[202:205], v[174:177], v[122:125]
	s_waitcnt lgkmcnt(1)
	v_mfma_f32_16x16x32_bf16 v[94:97], v[198:201], v[218:221], v[94:97]
	v_mfma_f32_16x16x32_bf16 v[10:13], v[144:147], v[190:193], v[10:13]
	ds_read_b128 v[144:147], v29 offset:8192
	ds_read_b128 v[226:229], v29 offset:10240
	ds_read_b128 v[230:233], v29 offset:12288
	ds_read_b128 v[234:237], v29 offset:14336
	v_lshlrev_b32_e32 v29, 9, v154
	v_and_or_b32 v152, v28, 8, v29
	v_mfma_f32_16x16x32_bf16 v[118:121], v[206:209], v[174:177], v[118:121]
	v_cvt_pk_bf16_f32 v28, v126, v127
	v_lshrrev_b32_e32 v126, 3, v153
	v_xor_b32_e32 v127, v126, v151
	v_mfma_f32_16x16x32_bf16 v[90:93], v[202:205], v[218:221], v[90:93]
	v_cvt_pk_bf16_f32 v29, v128, v129
	v_lshl_or_b32 v127, v127, 4, v152
	v_cvt_pk_bf16_f32 v122, v122, v123
	v_mfma_f32_16x16x32_bf16 v[114:117], v[210:213], v[174:177], v[114:117]
	v_cvt_pk_bf16_f32 v123, v124, v125
	v_bitop3_b32 v124, v126, v151, 2 bitop3:0x36
	v_cvt_pk_bf16_f32 v94, v94, v95
	v_mfma_f32_16x16x32_bf16 v[86:89], v[206:209], v[218:221], v[86:89]
	v_cvt_pk_bf16_f32 v95, v96, v97
	s_waitcnt lgkmcnt(0)
	s_barrier
; DEV unsigned cvt_pk_bf16(float lo, float hi) { const f32x2_t v = {lo, hi}; const bf16x2_t b = __builtin_convertvector(v, bf16x2_t); return __builtin_bit_cast(unsigned, b); }
; template <class Epi>
; DEV void gemm256_tile(const bf16_t* __restrict__ A, int lda, const bf16_t* __restrict__ Bt, int ldb, int K, unsigned char* lds, const Epi& epi) {
;     ...
;                 for (int mi = 0; mi < 4; ++mi)
; #pragma unroll
;                     for (int ni = 0; ni < 4; ++ni) acc[mh * 4 + mi][ni] = __builtin_amdgcn_mfma_f32_16x16x32_bf16(bfr[ni], af[mi], acc[mh * 4 + mi][ni], 0, 0, 0);
;             }
;         }
;     }
;     ...
;     __syncthreads();
;     if constexpr (Epi::STAGE) {
; #pragma unroll
;         for (int mi = 0; mi < 8; ++mi)
; #pragma unroll
;             for (int ni = 0; ni < 4; ++ni) {
;                 const int row = wr * 128 + mi * 16 + fr, col = wc * 64 + ni * 16 + fq * 4;
;                 const f32x4 v = epi.xform(row, col, acc[mi][ni]);
;                 uint2 w; w.x = cvt_pk_bf16(v[0], v[1]); w.y = cvt_pk_bf16(v[2], v[3]);
;                 *(uint2*)(lds + row * 512 + ((((col >> 3) ^ (row & 31)) << 4) | (((col >> 2) & 1) << 3))) = w;
;             }
;         __syncthreads();
	v_mfma_f32_16x16x32_bf16 v[110:113], v[198:201], v[214:217], v[110:113]
	v_lshl_add_u32 v124, v124, 4, v152
	v_cvt_pk_bf16_f32 v118, v118, v119
	v_mfma_f32_16x16x32_bf16 v[82:85], v[210:213], v[218:221], v[82:85]
	v_cvt_pk_bf16_f32 v119, v120, v121
	v_bitop3_b32 v120, v126, v151, 4 bitop3:0x36
	ds_write2st64_b64 v127, v[28:29], v[94:95] offset1:32
	v_mfma_f32_16x16x32_bf16 v[106:109], v[202:205], v[214:217], v[106:109]
	v_cvt_pk_bf16_f32 v28, v90, v91
	v_cvt_pk_bf16_f32 v29, v92, v93
	v_lshl_add_u32 v120, v120, 4, v152
	v_mfma_f32_16x16x32_bf16 v[78:81], v[198:201], v[222:225], v[78:81]
	v_cvt_pk_bf16_f32 v114, v114, v115
	v_cvt_pk_bf16_f32 v115, v116, v117
	v_bitop3_b32 v116, v126, v151, 6 bitop3:0x36
	v_mfma_f32_16x16x32_bf16 v[102:105], v[206:209], v[214:217], v[102:105]
	ds_write2st64_b64 v124, v[122:123], v[28:29] offset1:32
	v_cvt_pk_bf16_f32 v28, v86, v87
	v_cvt_pk_bf16_f32 v29, v88, v89
	v_mfma_f32_16x16x32_bf16 v[74:77], v[202:205], v[222:225], v[74:77]
	v_lshl_add_u32 v116, v116, 4, v152
	v_or_b32_e32 v117, 16, v151
	v_cvt_pk_bf16_f32 v110, v110, v111
	v_mfma_f32_16x16x32_bf16 v[2:5], v[182:185], v[190:193], v[2:5]
	v_cvt_pk_bf16_f32 v111, v112, v113
	v_bitop3_b32 v112, v126, v151, 16 bitop3:0x1e
	ds_write2st64_b64 v120, v[118:119], v[28:29] offset1:32
	v_mfma_f32_16x16x32_bf16 v[98:101], v[210:213], v[214:217], v[98:101]
	v_cvt_pk_bf16_f32 v28, v82, v83
	v_cvt_pk_bf16_f32 v29, v84, v85
	v_lshl_or_b32 v112, v112, 4, v152
	v_mfma_f32_16x16x32_bf16 v[70:73], v[206:209], v[222:225], v[70:73]
	v_cvt_pk_bf16_f32 v106, v106, v107
	v_cvt_pk_bf16_f32 v107, v108, v109
	v_bitop3_b32 v108, v126, v117, 2 bitop3:0x36
	v_mfma_f32_16x16x32_bf16 v[66:69], v[210:213], v[222:225], v[66:69]
	ds_write2st64_b64 v116, v[114:115], v[28:29] offset1:32
	v_cvt_pk_bf16_f32 v28, v78, v79
	v_cvt_pk_bf16_f32 v29, v80, v81
	v_lshl_add_u32 v108, v108, 4, v152
	v_cvt_pk_bf16_f32 v102, v102, v103
	v_cvt_pk_bf16_f32 v103, v104, v105
	v_bitop3_b32 v104, v126, v117, 4 bitop3:0x36
	ds_write2st64_b64 v112, v[110:111], v[28:29] offset0:16 offset1:48
	v_cvt_pk_bf16_f32 v28, v74, v75
	v_cvt_pk_bf16_f32 v29, v76, v77
	v_lshl_add_u32 v104, v104, 4, v152
	v_cvt_pk_bf16_f32 v98, v98, v99
	v_cvt_pk_bf16_f32 v99, v100, v101
	v_bitop3_b32 v100, v126, v117, 6 bitop3:0x36
	ds_write2st64_b64 v108, v[106:107], v[28:29] offset0:16 offset1:48
	v_cvt_pk_bf16_f32 v28, v70, v71
	v_cvt_pk_bf16_f32 v29, v72, v73
	v_mfma_f32_16x16x32_bf16 v[34:37], v[206:209], v[226:229], v[34:37]
	v_lshl_add_u32 v100, v100, 4, v152
	ds_write2st64_b64 v104, v[102:103], v[28:29] offset0:16 offset1:48
	v_cvt_pk_bf16_f32 v28, v66, v67
	v_mfma_f32_16x16x32_bf16 v[2:5], v[206:209], v[234:237], v[2:5]
	v_cvt_pk_bf16_f32 v29, v68, v69
	ds_write2st64_b64 v100, v[98:99], v[28:29] offset0:16 offset1:48
	s_nop 1
	v_cvt_pk_bf16_f32 v34, v34, v35
	v_mfma_f32_16x16x32_bf16 v[38:41], v[186:189], v[190:193], v[38:41]
	v_cvt_pk_bf16_f32 v35, v36, v37
	s_nop 0
	v_cvt_pk_bf16_f32 v2, v2, v3
	v_cvt_pk_bf16_f32 v3, v4, v5
	v_mfma_f32_16x16x32_bf16 v[6:9], v[178:181], v[190:193], v[6:9]
	ds_write2st64_b64 v104, v[34:35], v[2:3] offset0:80 offset1:112
	v_mfma_f32_16x16x32_bf16 v[28:31], v[210:213], v[226:229], v[30:33]
	v_mfma_f32_16x16x32_bf16 v[2:5], v[210:213], v[234:237], v[38:41]
	v_mfma_f32_16x16x32_bf16 v[62:65], v[198:201], v[144:147], v[62:65]
	s_nop 5
	v_cvt_pk_bf16_f32 v32, v28, v29
	v_cvt_pk_bf16_f32 v33, v30, v31
	v_cvt_pk_bf16_f32 v2, v2, v3
	v_mfma_f32_16x16x32_bf16 v[58:61], v[202:205], v[144:147], v[58:61]
	v_cvt_pk_bf16_f32 v3, v4, v5
	v_cvt_pk_bf16_f32 v62, v62, v63
	v_cvt_pk_bf16_f32 v63, v64, v65
	v_mfma_f32_16x16x32_bf16 v[54:57], v[206:209], v[144:147], v[54:57]
	ds_write2st64_b64 v100, v[32:33], v[2:3] offset0:80 offset1:112
	s_nop 2
	v_cvt_pk_bf16_f32 v58, v58, v59
	v_cvt_pk_bf16_f32 v59, v60, v61
	v_mfma_f32_16x16x32_bf16 v[50:53], v[210:213], v[144:147], v[50:53]
	v_and_b32_e32 v2, 0x1f0, v142
	v_cvt_pk_bf16_f32 v54, v54, v55
	v_cvt_pk_bf16_f32 v55, v56, v57
	v_mfma_f32_16x16x32_bf16 v[46:49], v[198:201], v[226:229], v[46:49]
	v_mfma_f32_16x16x32_bf16 v[42:45], v[202:205], v[226:229], v[42:45]
	s_nop 2
	v_cvt_pk_bf16_f32 v50, v50, v51
	v_cvt_pk_bf16_f32 v51, v52, v53
	s_nop 1
	v_cvt_pk_bf16_f32 v46, v46, v47
	v_mfma_f32_16x16x32_bf16 v[28:31], v[198:201], v[230:233], v[194:197]
	v_cvt_pk_bf16_f32 v47, v48, v49
	v_cvt_pk_bf16_f32 v42, v42, v43
	v_cvt_pk_bf16_f32 v43, v44, v45
	v_mfma_f32_16x16x32_bf16 v[22:25], v[202:205], v[230:233], v[22:25]
	v_mfma_f32_16x16x32_bf16 v[18:21], v[206:209], v[230:233], v[18:21]
	s_nop 2
	v_cvt_pk_bf16_f32 v28, v28, v29
	v_cvt_pk_bf16_f32 v29, v30, v31
	s_nop 1
	v_cvt_pk_bf16_f32 v22, v22, v23
	v_mfma_f32_16x16x32_bf16 v[14:17], v[210:213], v[230:233], v[14:17]
	v_cvt_pk_bf16_f32 v23, v24, v25
	v_cvt_pk_bf16_f32 v18, v18, v19
	v_cvt_pk_bf16_f32 v19, v20, v21
	v_mfma_f32_16x16x32_bf16 v[10:13], v[198:201], v[234:237], v[10:13]
	ds_write2st64_b64 v127, v[62:63], v[28:29] offset0:64 offset1:96
	s_nop 2
	v_cvt_pk_bf16_f32 v14, v14, v15
	v_cvt_pk_bf16_f32 v15, v16, v17
	v_mfma_f32_16x16x32_bf16 v[6:9], v[202:205], v[234:237], v[6:9]
	ds_write2st64_b64 v124, v[58:59], v[22:23] offset0:64 offset1:96
	v_cvt_pk_bf16_f32 v10, v10, v11
	v_cvt_pk_bf16_f32 v11, v12, v13
	ds_write2st64_b64 v120, v[54:55], v[18:19] offset0:64 offset1:96
	ds_write2st64_b64 v116, v[50:51], v[14:15] offset0:64 offset1:96
	s_nop 2
	v_cvt_pk_bf16_f32 v6, v6, v7
	v_cvt_pk_bf16_f32 v7, v8, v9
	ds_write2st64_b64 v112, v[46:47], v[10:11] offset0:80 offset1:112
	ds_write2st64_b64 v108, v[42:43], v[6:7] offset0:80 offset1:112
	s_waitcnt lgkmcnt(0)
	s_barrier

.LBB0_1003:
	s_and_b32 s48, s25, 0x10000
	s_xor_b32 s49, s48, 0x10000
	v_add_u32_e32 v216, s49, v136
	v_add_u32_e32 v217, s49, v150
	s_waitcnt vmcnt(0) lgkmcnt(0)
	s_barrier
	v_readfirstlane_b32 s50, v138
	v_readfirstlane_b32 s51, v139
	v_readfirstlane_b32 s58, v140
	v_readfirstlane_b32 s59, v141
	v_or_b32_e32 v248, s48, v151
	v_add_u32_e32 v249, s48, v148
	v_add_u32_e32 v244, v248, v149
	v_add_u32_e32 v245, v249, v149
	ds_read_b128 v[152:155], v244 offset:32768
	ds_read_b128 v[176:179], v244 offset:34816
	ds_read_b128 v[180:183], v244 offset:36864
	ds_read_b128 v[184:187], v244 offset:38912
	ds_read_b128 v[228:231], v245
	ds_read_b128 v[232:235], v245 offset:2048
	ds_read_b128 v[236:239], v245 offset:4096
	ds_read_b128 v[240:243], v245 offset:6144
	v_readfirstlane_b32 s40, v216
	v_readfirstlane_b32 s44, v217
	v_subrev_u32_e32 v218, s50, v138
	v_subrev_u32_e32 v219, s58, v140
	v_add_u32_e32 v246, v248, v147
	v_add_u32_e32 v247, v249, v147
	s_mov_b32 m0, s40
	s_add_u32 s52, s50, s6
	s_addc_u32 s53, s51, s7
	global_load_lds_dwordx4 v218, s[50:51]
	s_mov_b32 m0, s44
	s_add_u32 s60, s58, s6
	s_addc_u32 s61, s59, s7
	global_load_lds_dwordx4 v219, s[58:59]
	s_add_i32 s41, s40, 0x2000
	s_add_i32 s45, s44, 0x2000
	s_add_i32 s42, s40, 0x4000
	s_add_i32 s46, s44, 0x4000
	s_add_i32 s43, s40, 0x6000
	s_add_i32 s47, s44, 0x6000
	s_add_i32 s25, s25, 0x10000
	s_waitcnt lgkmcnt(3)
	v_mfma_f32_16x16x32_bf16 v[126:129], v[152:155], v[228:231], v[126:129]
	s_add_u32 s54, s50, s8
	s_addc_u32 s55, s51, s9
	v_mfma_f32_16x16x32_bf16 v[122:125], v[176:179], v[228:231], v[122:125]
	s_add_u32 s62, s58, s8
	s_addc_u32 s63, s59, s9
	v_mfma_f32_16x16x32_bf16 v[118:121], v[180:183], v[228:231], v[118:121]
	s_add_u32 s56, s50, s10
	s_addc_u32 s57, s51, s11
	v_mfma_f32_16x16x32_bf16 v[114:117], v[184:187], v[228:231], v[114:117]
	s_add_u32 s64, s58, s10
	s_addc_u32 s65, s59, s11
	s_waitcnt lgkmcnt(2)
	v_mfma_f32_16x16x32_bf16 v[110:113], v[152:155], v[232:235], v[110:113]
	v_mfma_f32_16x16x32_bf16 v[106:109], v[176:179], v[232:235], v[106:109]
	v_mfma_f32_16x16x32_bf16 v[102:105], v[180:183], v[232:235], v[102:105]
	v_mfma_f32_16x16x32_bf16 v[98:101], v[184:187], v[232:235], v[98:101]
	s_waitcnt lgkmcnt(1)
	v_mfma_f32_16x16x32_bf16 v[94:97], v[152:155], v[236:239], v[94:97]
	ds_read_b128 v[228:231], v245 offset:8192
	v_mfma_f32_16x16x32_bf16 v[90:93], v[176:179], v[236:239], v[90:93]
	ds_read_b128 v[232:235], v245 offset:10240
	v_mfma_f32_16x16x32_bf16 v[86:89], v[180:183], v[236:239], v[86:89]
	s_mov_b32 m0, s41
	v_mfma_f32_16x16x32_bf16 v[82:85], v[184:187], v[236:239], v[82:85]
	global_load_lds_dwordx4 v218, s[52:53]
	s_waitcnt lgkmcnt(2)
	v_mfma_f32_16x16x32_bf16 v[78:81], v[152:155], v[240:243], v[78:81]
	s_mov_b32 m0, s45
	v_mfma_f32_16x16x32_bf16 v[74:77], v[176:179], v[240:243], v[74:77]
	global_load_lds_dwordx4 v219, s[60:61]
	v_mfma_f32_16x16x32_bf16 v[70:73], v[180:183], v[240:243], v[70:73]
	v_mfma_f32_16x16x32_bf16 v[66:69], v[184:187], v[240:243], v[66:69]
	s_waitcnt lgkmcnt(1)
	v_mfma_f32_16x16x32_bf16 v[62:65], v[152:155], v[228:231], v[62:65]
	ds_read_b128 v[236:239], v245 offset:12288
	v_mfma_f32_16x16x32_bf16 v[58:61], v[176:179], v[228:231], v[58:61]
	ds_read_b128 v[240:243], v245 offset:14336
	v_mfma_f32_16x16x32_bf16 v[54:57], v[180:183], v[228:231], v[54:57]
	s_mov_b32 m0, s42
	v_mfma_f32_16x16x32_bf16 v[50:53], v[184:187], v[228:231], v[50:53]
	global_load_lds_dwordx4 v218, s[54:55]
	s_waitcnt lgkmcnt(2)
	v_mfma_f32_16x16x32_bf16 v[46:49], v[152:155], v[232:235], v[46:49]
	s_mov_b32 m0, s46
	v_mfma_f32_16x16x32_bf16 v[42:45], v[176:179], v[232:235], v[42:45]
	global_load_lds_dwordx4 v219, s[62:63]
	v_mfma_f32_16x16x32_bf16 v[34:37], v[180:183], v[232:235], v[34:37]
	v_mfma_f32_16x16x32_bf16 v[30:33], v[184:187], v[232:235], v[30:33]
	s_waitcnt lgkmcnt(1)
	v_mfma_f32_16x16x32_bf16 v[26:29], v[152:155], v[236:239], v[26:29]
	ds_read_b128 v[188:191], v246 offset:32768
	v_mfma_f32_16x16x32_bf16 v[22:25], v[176:179], v[236:239], v[22:25]
	ds_read_b128 v[192:195], v246 offset:34816
	v_mfma_f32_16x16x32_bf16 v[18:21], v[180:183], v[236:239], v[18:21]
	ds_read_b128 v[220:223], v246 offset:36864
	v_mfma_f32_16x16x32_bf16 v[14:17], v[184:187], v[236:239], v[14:17]
	ds_read_b128 v[224:227], v246 offset:38912
	s_waitcnt lgkmcnt(4)
	v_mfma_f32_16x16x32_bf16 v[10:13], v[152:155], v[240:243], v[10:13]
	ds_read_b128 v[228:231], v247
	v_mfma_f32_16x16x32_bf16 v[6:9], v[176:179], v[240:243], v[6:9]
	ds_read_b128 v[232:235], v247 offset:2048
	v_mfma_f32_16x16x32_bf16 v[2:5], v[180:183], v[240:243], v[2:5]
	s_mov_b32 m0, s43
	v_mfma_f32_16x16x32_bf16 v[38:41], v[184:187], v[240:243], v[38:41]
	global_load_lds_dwordx4 v218, s[56:57]
	s_mov_b32 m0, s47
	v_lshl_add_u64 v[138:139], v[138:139], 0, s[12:13]
	global_load_lds_dwordx4 v219, s[64:65]
	v_lshl_add_u64 v[140:141], v[140:141], 0, s[12:13]
	s_waitcnt lgkmcnt(1)
	v_mfma_f32_16x16x32_bf16 v[126:129], v[188:191], v[228:231], v[126:129]
	ds_read_b128 v[236:239], v247 offset:4096
	v_mfma_f32_16x16x32_bf16 v[122:125], v[192:195], v[228:231], v[122:125]
	ds_read_b128 v[240:243], v247 offset:6144
	v_mfma_f32_16x16x32_bf16 v[118:121], v[220:223], v[228:231], v[118:121]
	v_mfma_f32_16x16x32_bf16 v[114:117], v[224:227], v[228:231], v[114:117]
	s_waitcnt lgkmcnt(2)
	v_mfma_f32_16x16x32_bf16 v[110:113], v[188:191], v[232:235], v[110:113]
	v_mfma_f32_16x16x32_bf16 v[106:109], v[192:195], v[232:235], v[106:109]
	v_mfma_f32_16x16x32_bf16 v[102:105], v[220:223], v[232:235], v[102:105]
	v_mfma_f32_16x16x32_bf16 v[98:101], v[224:227], v[232:235], v[98:101]
	s_waitcnt lgkmcnt(1)
	v_mfma_f32_16x16x32_bf16 v[94:97], v[188:191], v[236:239], v[94:97]
	ds_read_b128 v[228:231], v247 offset:8192
	v_mfma_f32_16x16x32_bf16 v[90:93], v[192:195], v[236:239], v[90:93]
	ds_read_b128 v[232:235], v247 offset:10240
	v_mfma_f32_16x16x32_bf16 v[86:89], v[220:223], v[236:239], v[86:89]
	v_mfma_f32_16x16x32_bf16 v[82:85], v[224:227], v[236:239], v[82:85]
	s_waitcnt lgkmcnt(2)
	v_mfma_f32_16x16x32_bf16 v[78:81], v[188:191], v[240:243], v[78:81]
	v_mfma_f32_16x16x32_bf16 v[74:77], v[192:195], v[240:243], v[74:77]
	v_mfma_f32_16x16x32_bf16 v[70:73], v[220:223], v[240:243], v[70:73]
	v_mfma_f32_16x16x32_bf16 v[66:69], v[224:227], v[240:243], v[66:69]
	s_waitcnt lgkmcnt(1)
	v_mfma_f32_16x16x32_bf16 v[62:65], v[188:191], v[228:231], v[62:65]
	ds_read_b128 v[236:239], v247 offset:12288
	v_mfma_f32_16x16x32_bf16 v[58:61], v[192:195], v[228:231], v[58:61]
	ds_read_b128 v[240:243], v247 offset:14336
	v_mfma_f32_16x16x32_bf16 v[54:57], v[220:223], v[228:231], v[54:57]
	v_mfma_f32_16x16x32_bf16 v[50:53], v[224:227], v[228:231], v[50:53]
	s_waitcnt lgkmcnt(2)
	v_mfma_f32_16x16x32_bf16 v[46:49], v[188:191], v[232:235], v[46:49]
	v_mfma_f32_16x16x32_bf16 v[42:45], v[192:195], v[232:235], v[42:45]
	v_mfma_f32_16x16x32_bf16 v[34:37], v[220:223], v[232:235], v[34:37]
	v_mfma_f32_16x16x32_bf16 v[30:33], v[224:227], v[232:235], v[30:33]
	s_waitcnt lgkmcnt(1)
	v_mfma_f32_16x16x32_bf16 v[26:29], v[188:191], v[236:239], v[26:29]
	v_mfma_f32_16x16x32_bf16 v[22:25], v[192:195], v[236:239], v[22:25]
	v_mfma_f32_16x16x32_bf16 v[18:21], v[220:223], v[236:239], v[18:21]
	v_mfma_f32_16x16x32_bf16 v[14:17], v[224:227], v[236:239], v[14:17]
	s_waitcnt lgkmcnt(0)
	v_mfma_f32_16x16x32_bf16 v[10:13], v[188:191], v[240:243], v[10:13]
	v_mfma_f32_16x16x32_bf16 v[6:9], v[192:195], v[240:243], v[6:9]
	v_mfma_f32_16x16x32_bf16 v[2:5], v[220:223], v[240:243], v[2:5]
	v_mfma_f32_16x16x32_bf16 v[38:41], v[224:227], v[240:243], v[38:41]
	s_cmp_eq_u32 s25, 0x1f0000
	s_cbranch_scc0 .LBB0_1003
	v_or_b32_e32 v172, 0x18000, v151
	v_add_u32_e32 v156, v172, v149
	s_waitcnt vmcnt(0)
	s_barrier
	ds_read_b128 v[138:141], v156
	ds_read_b128 v[152:155], v156 offset:2048
	ds_read_b128 v[176:179], v156 offset:4096
	ds_read_b128 v[180:183], v156 offset:6144
	v_add_u32_e32 v173, 0x10000, v148
	v_add_u32_e32 v188, v173, v149
	ds_read_b128 v[148:151], v188
	s_waitcnt lgkmcnt(0)
	v_mfma_f32_16x16x32_bf16 v[126:129], v[138:141], v[148:151], v[126:129]
	s_sext_i32_i8 s14, s24
	s_lshl_b32 s24, s14, 8
	s_lshl_b64 s[16:17], s[16:17], 21
	v_mfma_f32_16x16x32_bf16 v[122:125], v[152:155], v[148:151], v[122:125]
	s_ashr_i32 s25, s24, 31
	s_add_u32 s14, s4, s16
	s_addc_u32 s15, s5, s17
	v_mfma_f32_16x16x32_bf16 v[118:121], v[176:179], v[148:151], v[118:121]
	s_lshl_b64 s[16:17], s[24:25], 2
	v_lshl_add_u64 v[156:157], v[130:131], 0, s[18:19]
	s_add_u32 s16, s14, s16
	v_mfma_f32_16x16x32_bf16 v[114:117], v[180:183], v[148:151], v[114:117]
	ds_read_b128 v[148:151], v188 offset:2048
	s_addc_u32 s17, s15, s17
	s_mov_b32 s18, 0
	s_waitcnt lgkmcnt(0)
	v_mfma_f32_16x16x32_bf16 v[110:113], v[138:141], v[148:151], v[110:113]
	v_mfma_f32_16x16x32_bf16 v[106:109], v[152:155], v[148:151], v[106:109]
	v_mfma_f32_16x16x32_bf16 v[102:105], v[176:179], v[148:151], v[102:105]
	v_mfma_f32_16x16x32_bf16 v[98:101], v[180:183], v[148:151], v[98:101]
	ds_read_b128 v[148:151], v188 offset:4096
	s_waitcnt lgkmcnt(0)
	v_mfma_f32_16x16x32_bf16 v[94:97], v[138:141], v[148:151], v[94:97]
	v_mfma_f32_16x16x32_bf16 v[90:93], v[152:155], v[148:151], v[90:93]
	v_mfma_f32_16x16x32_bf16 v[86:89], v[176:179], v[148:151], v[86:89]
	v_mfma_f32_16x16x32_bf16 v[82:85], v[180:183], v[148:151], v[82:85]
	ds_read_b128 v[148:151], v188 offset:6144
	s_waitcnt lgkmcnt(0)
	v_mfma_f32_16x16x32_bf16 v[78:81], v[138:141], v[148:151], v[78:81]
	v_mfma_f32_16x16x32_bf16 v[74:77], v[152:155], v[148:151], v[74:77]
	v_mfma_f32_16x16x32_bf16 v[70:73], v[176:179], v[148:151], v[70:73]
	v_mfma_f32_16x16x32_bf16 v[66:69], v[180:183], v[148:151], v[66:69]
	ds_read_b128 v[148:151], v188 offset:8192
	ds_read_b128 v[184:187], v188 offset:10240
	s_waitcnt lgkmcnt(1)
	v_mfma_f32_16x16x32_bf16 v[62:65], v[138:141], v[148:151], v[62:65]
	v_mfma_f32_16x16x32_bf16 v[58:61], v[152:155], v[148:151], v[58:61]
	v_mfma_f32_16x16x32_bf16 v[54:57], v[176:179], v[148:151], v[54:57]
	v_mfma_f32_16x16x32_bf16 v[50:53], v[180:183], v[148:151], v[50:53]
	ds_read_b128 v[148:151], v188 offset:12288
	s_waitcnt lgkmcnt(1)
	v_mfma_f32_16x16x32_bf16 v[46:49], v[138:141], v[184:187], v[46:49]
	v_mfma_f32_16x16x32_bf16 v[42:45], v[152:155], v[184:187], v[42:45]
	v_mfma_f32_16x16x32_bf16 v[34:37], v[176:179], v[184:187], v[34:37]
	v_mfma_f32_16x16x32_bf16 v[30:33], v[180:183], v[184:187], v[30:33]
	ds_read_b128 v[184:187], v188 offset:14336
	s_waitcnt lgkmcnt(1)
	v_mfma_f32_16x16x32_bf16 v[188:191], v[138:141], v[148:151], v[26:29]
	s_nop 2
	v_add_u32_e32 v29, v172, v147
	ds_read_b128 v[192:195], v29
	ds_read_b128 v[196:199], v29 offset:2048
	ds_read_b128 v[200:203], v29 offset:4096
	ds_read_b128 v[204:207], v29 offset:6144
	v_add_u32_e32 v29, v173, v147
	v_mfma_f32_16x16x32_bf16 v[22:25], v[152:155], v[148:151], v[22:25]
	v_and_b32_e32 v28, 0xc0, v142
	v_lshl_or_b32 v145, v145, 2, v28
	v_lshlrev_b32_e32 v28, 3, v144
	v_mfma_f32_16x16x32_bf16 v[18:21], v[176:179], v[148:151], v[18:21]
	v_lshl_add_u64 v[26:27], s[24:25], 1, v[156:157]
	v_mfma_f32_16x16x32_bf16 v[14:17], v[180:183], v[148:151], v[14:17]
	ds_read_b128 v[148:151], v29
	ds_read_b128 v[208:211], v29 offset:2048
	ds_read_b128 v[212:215], v29 offset:4096
	ds_read_b128 v[216:219], v29 offset:6144
	s_waitcnt lgkmcnt(3)
	v_mfma_f32_16x16x32_bf16 v[126:129], v[192:195], v[148:151], v[126:129]
	v_mfma_f32_16x16x32_bf16 v[122:125], v[196:199], v[148:151], v[122:125]
	s_waitcnt lgkmcnt(1)
	v_mfma_f32_16x16x32_bf16 v[94:97], v[192:195], v[212:215], v[94:97]
	v_mfma_f32_16x16x32_bf16 v[10:13], v[138:141], v[184:187], v[10:13]
	ds_read_b128 v[138:141], v29 offset:8192
	ds_read_b128 v[220:223], v29 offset:10240
	ds_read_b128 v[224:227], v29 offset:12288
	ds_read_b128 v[228:231], v29 offset:14336
	v_lshlrev_b32_e32 v29, 9, v146
	v_and_or_b32 v144, v28, 8, v29
	v_mfma_f32_16x16x32_bf16 v[118:121], v[200:203], v[148:151], v[118:121]
	v_cvt_pk_bf16_f32 v28, v126, v127
	v_lshrrev_b32_e32 v126, 3, v145
	v_xor_b32_e32 v127, v126, v143
	v_mfma_f32_16x16x32_bf16 v[90:93], v[196:199], v[212:215], v[90:93]
	v_cvt_pk_bf16_f32 v29, v128, v129
	v_lshl_or_b32 v127, v127, 4, v144
	v_cvt_pk_bf16_f32 v122, v122, v123
	v_mfma_f32_16x16x32_bf16 v[114:117], v[204:207], v[148:151], v[114:117]
	v_cvt_pk_bf16_f32 v123, v124, v125
	v_bitop3_b32 v124, v126, v143, 2 bitop3:0x36
	v_cvt_pk_bf16_f32 v94, v94, v95
	v_mfma_f32_16x16x32_bf16 v[86:89], v[200:203], v[212:215], v[86:89]
	v_cvt_pk_bf16_f32 v95, v96, v97
	s_waitcnt lgkmcnt(0)
	s_barrier
	v_mfma_f32_16x16x32_bf16 v[110:113], v[192:195], v[208:211], v[110:113]
	v_lshl_add_u32 v124, v124, 4, v144
	v_cvt_pk_bf16_f32 v118, v118, v119
	v_mfma_f32_16x16x32_bf16 v[82:85], v[204:207], v[212:215], v[82:85]
	v_cvt_pk_bf16_f32 v119, v120, v121
	v_bitop3_b32 v120, v126, v143, 4 bitop3:0x36
	ds_write2st64_b64 v127, v[28:29], v[94:95] offset1:32
	v_mfma_f32_16x16x32_bf16 v[106:109], v[196:199], v[208:211], v[106:109]
	v_cvt_pk_bf16_f32 v28, v90, v91
	v_cvt_pk_bf16_f32 v29, v92, v93
	v_lshl_add_u32 v120, v120, 4, v144
	v_mfma_f32_16x16x32_bf16 v[78:81], v[192:195], v[216:219], v[78:81]
	v_cvt_pk_bf16_f32 v114, v114, v115
	v_cvt_pk_bf16_f32 v115, v116, v117
	v_bitop3_b32 v116, v126, v143, 6 bitop3:0x36
	v_mfma_f32_16x16x32_bf16 v[102:105], v[200:203], v[208:211], v[102:105]
	ds_write2st64_b64 v124, v[122:123], v[28:29] offset1:32
	v_cvt_pk_bf16_f32 v28, v86, v87
	v_cvt_pk_bf16_f32 v29, v88, v89
	v_mfma_f32_16x16x32_bf16 v[74:77], v[196:199], v[216:219], v[74:77]
	v_lshl_add_u32 v116, v116, 4, v144
	v_or_b32_e32 v117, 16, v143
	v_cvt_pk_bf16_f32 v110, v110, v111
	v_mfma_f32_16x16x32_bf16 v[2:5], v[176:179], v[184:187], v[2:5]
	v_cvt_pk_bf16_f32 v111, v112, v113
	v_bitop3_b32 v112, v126, v143, 16 bitop3:0x1e
	ds_write2st64_b64 v120, v[118:119], v[28:29] offset1:32
	v_mfma_f32_16x16x32_bf16 v[98:101], v[204:207], v[208:211], v[98:101]
	v_cvt_pk_bf16_f32 v28, v82, v83
	v_cvt_pk_bf16_f32 v29, v84, v85
	v_lshl_or_b32 v112, v112, 4, v144
	v_mfma_f32_16x16x32_bf16 v[70:73], v[200:203], v[216:219], v[70:73]
	v_cvt_pk_bf16_f32 v106, v106, v107
	v_cvt_pk_bf16_f32 v107, v108, v109
	v_bitop3_b32 v108, v126, v117, 2 bitop3:0x36
	v_mfma_f32_16x16x32_bf16 v[66:69], v[204:207], v[216:219], v[66:69]
	ds_write2st64_b64 v116, v[114:115], v[28:29] offset1:32
	v_cvt_pk_bf16_f32 v28, v78, v79
	v_cvt_pk_bf16_f32 v29, v80, v81
	v_lshl_add_u32 v108, v108, 4, v144
	v_cvt_pk_bf16_f32 v102, v102, v103
	v_cvt_pk_bf16_f32 v103, v104, v105
	v_bitop3_b32 v104, v126, v117, 4 bitop3:0x36
	ds_write2st64_b64 v112, v[110:111], v[28:29] offset0:16 offset1:48
	v_cvt_pk_bf16_f32 v28, v74, v75
	v_cvt_pk_bf16_f32 v29, v76, v77
	v_lshl_add_u32 v104, v104, 4, v144
	v_cvt_pk_bf16_f32 v98, v98, v99
	v_cvt_pk_bf16_f32 v99, v100, v101
	v_bitop3_b32 v100, v126, v117, 6 bitop3:0x36
	ds_write2st64_b64 v108, v[106:107], v[28:29] offset0:16 offset1:48
	v_cvt_pk_bf16_f32 v28, v70, v71
	v_cvt_pk_bf16_f32 v29, v72, v73
	v_mfma_f32_16x16x32_bf16 v[34:37], v[200:203], v[220:223], v[34:37]
	v_lshl_add_u32 v100, v100, 4, v144
	ds_write2st64_b64 v104, v[102:103], v[28:29] offset0:16 offset1:48
	v_cvt_pk_bf16_f32 v28, v66, v67
	v_mfma_f32_16x16x32_bf16 v[2:5], v[200:203], v[228:231], v[2:5]
	v_cvt_pk_bf16_f32 v29, v68, v69
	ds_write2st64_b64 v100, v[98:99], v[28:29] offset0:16 offset1:48
	s_nop 1
	v_cvt_pk_bf16_f32 v34, v34, v35
	v_mfma_f32_16x16x32_bf16 v[38:41], v[180:183], v[184:187], v[38:41]
	v_cvt_pk_bf16_f32 v35, v36, v37
	s_nop 0
	v_cvt_pk_bf16_f32 v2, v2, v3
	v_cvt_pk_bf16_f32 v3, v4, v5
	v_mfma_f32_16x16x32_bf16 v[6:9], v[152:155], v[184:187], v[6:9]
	ds_write2st64_b64 v104, v[34:35], v[2:3] offset0:80 offset1:112
	v_mfma_f32_16x16x32_bf16 v[28:31], v[204:207], v[220:223], v[30:33]
	v_mfma_f32_16x16x32_bf16 v[2:5], v[204:207], v[228:231], v[38:41]
	v_mfma_f32_16x16x32_bf16 v[62:65], v[192:195], v[138:141], v[62:65]
	s_nop 5
	v_cvt_pk_bf16_f32 v32, v28, v29
	v_cvt_pk_bf16_f32 v33, v30, v31
	v_cvt_pk_bf16_f32 v2, v2, v3
	v_mfma_f32_16x16x32_bf16 v[58:61], v[196:199], v[138:141], v[58:61]
	v_cvt_pk_bf16_f32 v3, v4, v5
	v_cvt_pk_bf16_f32 v62, v62, v63
	v_cvt_pk_bf16_f32 v63, v64, v65
	v_mfma_f32_16x16x32_bf16 v[54:57], v[200:203], v[138:141], v[54:57]
	ds_write2st64_b64 v100, v[32:33], v[2:3] offset0:80 offset1:112
	s_nop 2
	v_cvt_pk_bf16_f32 v58, v58, v59
	v_cvt_pk_bf16_f32 v59, v60, v61
	v_mfma_f32_16x16x32_bf16 v[50:53], v[204:207], v[138:141], v[50:53]
	v_and_b32_e32 v2, 0x1f0, v136
	v_cvt_pk_bf16_f32 v54, v54, v55
	v_cvt_pk_bf16_f32 v55, v56, v57
	v_mfma_f32_16x16x32_bf16 v[46:49], v[192:195], v[220:223], v[46:49]
	v_mfma_f32_16x16x32_bf16 v[42:45], v[196:199], v[220:223], v[42:45]
	s_nop 2
	v_cvt_pk_bf16_f32 v50, v50, v51
	v_cvt_pk_bf16_f32 v51, v52, v53
	s_nop 1
	v_cvt_pk_bf16_f32 v46, v46, v47
	v_mfma_f32_16x16x32_bf16 v[28:31], v[192:195], v[224:227], v[188:191]
	v_cvt_pk_bf16_f32 v47, v48, v49
	v_cvt_pk_bf16_f32 v42, v42, v43
	v_cvt_pk_bf16_f32 v43, v44, v45
	v_mfma_f32_16x16x32_bf16 v[22:25], v[196:199], v[224:227], v[22:25]
	v_mfma_f32_16x16x32_bf16 v[18:21], v[200:203], v[224:227], v[18:21]
	s_nop 2
	v_cvt_pk_bf16_f32 v28, v28, v29
	v_cvt_pk_bf16_f32 v29, v30, v31
	s_nop 1
	v_cvt_pk_bf16_f32 v22, v22, v23
	v_mfma_f32_16x16x32_bf16 v[14:17], v[204:207], v[224:227], v[14:17]
	v_cvt_pk_bf16_f32 v23, v24, v25
	v_cvt_pk_bf16_f32 v18, v18, v19
	v_cvt_pk_bf16_f32 v19, v20, v21
	v_mfma_f32_16x16x32_bf16 v[10:13], v[192:195], v[228:231], v[10:13]
	ds_write2st64_b64 v127, v[62:63], v[28:29] offset0:64 offset1:96
	s_nop 2
	v_cvt_pk_bf16_f32 v14, v14, v15
	v_cvt_pk_bf16_f32 v15, v16, v17
	v_mfma_f32_16x16x32_bf16 v[6:9], v[196:199], v[228:231], v[6:9]
	ds_write2st64_b64 v124, v[58:59], v[22:23] offset0:64 offset1:96
	v_cvt_pk_bf16_f32 v10, v10, v11
	v_cvt_pk_bf16_f32 v11, v12, v13
	ds_write2st64_b64 v120, v[54:55], v[18:19] offset0:64 offset1:96
	ds_write2st64_b64 v116, v[50:51], v[14:15] offset0:64 offset1:96
	s_nop 2
	v_cvt_pk_bf16_f32 v6, v6, v7
	v_cvt_pk_bf16_f32 v7, v8, v9
	ds_write2st64_b64 v112, v[46:47], v[10:11] offset0:80 offset1:112
	ds_write2st64_b64 v108, v[42:43], v[6:7] offset0:80 offset1:112
	s_waitcnt lgkmcnt(0)
	s_barrier

.LBB0_1236:
	s_and_b32 s48, s21, 0x10000
	s_xor_b32 s49, s48, 0x10000
	v_add_u32_e32 v216, s49, v138
	v_add_u32_e32 v217, s49, v150
	s_waitcnt vmcnt(0) lgkmcnt(0)
	s_barrier
	v_readfirstlane_b32 s50, v140
	v_readfirstlane_b32 s51, v141
	v_readfirstlane_b32 s58, v142
	v_readfirstlane_b32 s59, v143
	v_or_b32_e32 v248, s48, v153
	v_add_u32_e32 v249, s48, v151
	v_add_u32_e32 v244, v248, v152
	v_add_u32_e32 v245, v249, v152
	ds_read_b128 v[154:157], v244 offset:32768
	ds_read_b128 v[170:173], v244 offset:34816
	ds_read_b128 v[174:177], v244 offset:36864
	ds_read_b128 v[178:181], v244 offset:38912
	ds_read_b128 v[228:231], v245
	ds_read_b128 v[232:235], v245 offset:2048
	ds_read_b128 v[236:239], v245 offset:4096
	ds_read_b128 v[240:243], v245 offset:6144
	v_readfirstlane_b32 s40, v216
	v_readfirstlane_b32 s44, v217
	v_subrev_u32_e32 v218, s50, v140
	v_subrev_u32_e32 v219, s58, v142
	v_add_u32_e32 v246, v248, v149
	v_add_u32_e32 v247, v249, v149
	s_mov_b32 m0, s40
	s_add_u32 s52, s50, s4
	s_addc_u32 s53, s51, s5
	global_load_lds_dwordx4 v218, s[50:51]
	s_mov_b32 m0, s44
	s_add_u32 s60, s58, s4
	s_addc_u32 s61, s59, s5
	global_load_lds_dwordx4 v219, s[58:59]
	s_add_i32 s41, s40, 0x2000
	s_add_i32 s45, s44, 0x2000
	s_add_i32 s42, s40, 0x4000
	s_add_i32 s46, s44, 0x4000
	s_add_i32 s43, s40, 0x6000
	s_add_i32 s47, s44, 0x6000
	s_add_i32 s21, s21, 0x10000
	s_waitcnt lgkmcnt(3)
	v_mfma_f32_16x16x32_bf16 v[126:129], v[154:157], v[228:231], v[126:129]
	s_add_u32 s54, s50, s6
	s_addc_u32 s55, s51, s7
	v_mfma_f32_16x16x32_bf16 v[122:125], v[170:173], v[228:231], v[122:125]
	s_add_u32 s62, s58, s6
	s_addc_u32 s63, s59, s7
	v_mfma_f32_16x16x32_bf16 v[118:121], v[174:177], v[228:231], v[118:121]
	s_add_u32 s56, s50, s8
	s_addc_u32 s57, s51, s9
	v_mfma_f32_16x16x32_bf16 v[114:117], v[178:181], v[228:231], v[114:117]
	s_add_u32 s64, s58, s8
	s_addc_u32 s65, s59, s9
	s_waitcnt lgkmcnt(2)
	v_mfma_f32_16x16x32_bf16 v[110:113], v[154:157], v[232:235], v[110:113]
	v_mfma_f32_16x16x32_bf16 v[106:109], v[170:173], v[232:235], v[106:109]
	v_mfma_f32_16x16x32_bf16 v[102:105], v[174:177], v[232:235], v[102:105]
	v_mfma_f32_16x16x32_bf16 v[98:101], v[178:181], v[232:235], v[98:101]
	s_waitcnt lgkmcnt(1)
	v_mfma_f32_16x16x32_bf16 v[94:97], v[154:157], v[236:239], v[94:97]
	ds_read_b128 v[228:231], v245 offset:8192
	v_mfma_f32_16x16x32_bf16 v[90:93], v[170:173], v[236:239], v[90:93]
	ds_read_b128 v[232:235], v245 offset:10240
	v_mfma_f32_16x16x32_bf16 v[86:89], v[174:177], v[236:239], v[86:89]
	s_mov_b32 m0, s41
	v_mfma_f32_16x16x32_bf16 v[82:85], v[178:181], v[236:239], v[82:85]
	global_load_lds_dwordx4 v218, s[52:53]
	s_waitcnt lgkmcnt(2)
	v_mfma_f32_16x16x32_bf16 v[78:81], v[154:157], v[240:243], v[78:81]
	s_mov_b32 m0, s45
	v_mfma_f32_16x16x32_bf16 v[74:77], v[170:173], v[240:243], v[74:77]
	global_load_lds_dwordx4 v219, s[60:61]
	v_mfma_f32_16x16x32_bf16 v[70:73], v[174:177], v[240:243], v[70:73]
	v_mfma_f32_16x16x32_bf16 v[66:69], v[178:181], v[240:243], v[66:69]
	s_waitcnt lgkmcnt(1)
	v_mfma_f32_16x16x32_bf16 v[62:65], v[154:157], v[228:231], v[62:65]
	ds_read_b128 v[236:239], v245 offset:12288
	v_mfma_f32_16x16x32_bf16 v[58:61], v[170:173], v[228:231], v[58:61]
	ds_read_b128 v[240:243], v245 offset:14336
	v_mfma_f32_16x16x32_bf16 v[54:57], v[174:177], v[228:231], v[54:57]
	s_mov_b32 m0, s42
	v_mfma_f32_16x16x32_bf16 v[50:53], v[178:181], v[228:231], v[50:53]
	global_load_lds_dwordx4 v218, s[54:55]
	s_waitcnt lgkmcnt(2)
	v_mfma_f32_16x16x32_bf16 v[46:49], v[154:157], v[232:235], v[46:49]
	s_mov_b32 m0, s46
	v_mfma_f32_16x16x32_bf16 v[42:45], v[170:173], v[232:235], v[42:45]
	global_load_lds_dwordx4 v219, s[62:63]
	v_mfma_f32_16x16x32_bf16 v[34:37], v[174:177], v[232:235], v[34:37]
	v_mfma_f32_16x16x32_bf16 v[30:33], v[178:181], v[232:235], v[30:33]
	s_waitcnt lgkmcnt(1)
	v_mfma_f32_16x16x32_bf16 v[26:29], v[154:157], v[236:239], v[26:29]
	ds_read_b128 v[182:185], v246 offset:32768
	v_mfma_f32_16x16x32_bf16 v[22:25], v[170:173], v[236:239], v[22:25]
	ds_read_b128 v[186:189], v246 offset:34816
	v_mfma_f32_16x16x32_bf16 v[18:21], v[174:177], v[236:239], v[18:21]
	ds_read_b128 v[220:223], v246 offset:36864
	v_mfma_f32_16x16x32_bf16 v[14:17], v[178:181], v[236:239], v[14:17]
	ds_read_b128 v[224:227], v246 offset:38912
	s_waitcnt lgkmcnt(4)
	v_mfma_f32_16x16x32_bf16 v[10:13], v[154:157], v[240:243], v[10:13]
	ds_read_b128 v[228:231], v247
	v_mfma_f32_16x16x32_bf16 v[6:9], v[170:173], v[240:243], v[6:9]
	ds_read_b128 v[232:235], v247 offset:2048
	v_mfma_f32_16x16x32_bf16 v[2:5], v[174:177], v[240:243], v[2:5]
	s_mov_b32 m0, s43
	v_mfma_f32_16x16x32_bf16 v[38:41], v[178:181], v[240:243], v[38:41]
	global_load_lds_dwordx4 v218, s[56:57]
	s_mov_b32 m0, s47
	v_lshl_add_u64 v[140:141], v[140:141], 0, s[10:11]
	global_load_lds_dwordx4 v219, s[64:65]
	v_lshl_add_u64 v[142:143], v[142:143], 0, s[10:11]
	s_waitcnt lgkmcnt(1)
	v_mfma_f32_16x16x32_bf16 v[126:129], v[182:185], v[228:231], v[126:129]
	ds_read_b128 v[236:239], v247 offset:4096
	v_mfma_f32_16x16x32_bf16 v[122:125], v[186:189], v[228:231], v[122:125]
	ds_read_b128 v[240:243], v247 offset:6144
	v_mfma_f32_16x16x32_bf16 v[118:121], v[220:223], v[228:231], v[118:121]
	v_mfma_f32_16x16x32_bf16 v[114:117], v[224:227], v[228:231], v[114:117]
	s_waitcnt lgkmcnt(2)
	v_mfma_f32_16x16x32_bf16 v[110:113], v[182:185], v[232:235], v[110:113]
	v_mfma_f32_16x16x32_bf16 v[106:109], v[186:189], v[232:235], v[106:109]
	v_mfma_f32_16x16x32_bf16 v[102:105], v[220:223], v[232:235], v[102:105]
	v_mfma_f32_16x16x32_bf16 v[98:101], v[224:227], v[232:235], v[98:101]
	s_waitcnt lgkmcnt(1)
	v_mfma_f32_16x16x32_bf16 v[94:97], v[182:185], v[236:239], v[94:97]
	ds_read_b128 v[228:231], v247 offset:8192
	v_mfma_f32_16x16x32_bf16 v[90:93], v[186:189], v[236:239], v[90:93]
	ds_read_b128 v[232:235], v247 offset:10240
	v_mfma_f32_16x16x32_bf16 v[86:89], v[220:223], v[236:239], v[86:89]
	v_mfma_f32_16x16x32_bf16 v[82:85], v[224:227], v[236:239], v[82:85]
	s_waitcnt lgkmcnt(2)
	v_mfma_f32_16x16x32_bf16 v[78:81], v[182:185], v[240:243], v[78:81]
	v_mfma_f32_16x16x32_bf16 v[74:77], v[186:189], v[240:243], v[74:77]
	v_mfma_f32_16x16x32_bf16 v[70:73], v[220:223], v[240:243], v[70:73]
	v_mfma_f32_16x16x32_bf16 v[66:69], v[224:227], v[240:243], v[66:69]
	s_waitcnt lgkmcnt(1)
	v_mfma_f32_16x16x32_bf16 v[62:65], v[182:185], v[228:231], v[62:65]
	ds_read_b128 v[236:239], v247 offset:12288
	v_mfma_f32_16x16x32_bf16 v[58:61], v[186:189], v[228:231], v[58:61]
	ds_read_b128 v[240:243], v247 offset:14336
	v_mfma_f32_16x16x32_bf16 v[54:57], v[220:223], v[228:231], v[54:57]
	v_mfma_f32_16x16x32_bf16 v[50:53], v[224:227], v[228:231], v[50:53]
	s_waitcnt lgkmcnt(2)
	v_mfma_f32_16x16x32_bf16 v[46:49], v[182:185], v[232:235], v[46:49]
	v_mfma_f32_16x16x32_bf16 v[42:45], v[186:189], v[232:235], v[42:45]
	v_mfma_f32_16x16x32_bf16 v[34:37], v[220:223], v[232:235], v[34:37]
	v_mfma_f32_16x16x32_bf16 v[30:33], v[224:227], v[232:235], v[30:33]
	s_waitcnt lgkmcnt(1)
	v_mfma_f32_16x16x32_bf16 v[26:29], v[182:185], v[236:239], v[26:29]
	v_mfma_f32_16x16x32_bf16 v[22:25], v[186:189], v[236:239], v[22:25]
	v_mfma_f32_16x16x32_bf16 v[18:21], v[220:223], v[236:239], v[18:21]
	v_mfma_f32_16x16x32_bf16 v[14:17], v[224:227], v[236:239], v[14:17]
	s_waitcnt lgkmcnt(0)
	v_mfma_f32_16x16x32_bf16 v[10:13], v[182:185], v[240:243], v[10:13]
	v_mfma_f32_16x16x32_bf16 v[6:9], v[186:189], v[240:243], v[6:9]
	v_mfma_f32_16x16x32_bf16 v[2:5], v[220:223], v[240:243], v[2:5]
	v_mfma_f32_16x16x32_bf16 v[38:41], v[224:227], v[240:243], v[38:41]
	s_cmp_eq_u32 s21, 0x1f0000
	s_cbranch_scc0 .LBB0_1236
	v_or_b32_e32 v186, 0x18000, v153
	v_add_u32_e32 v202, 0x10000, v151
	v_add_u32_e32 v174, v186, v152
	v_add_u32_e32 v182, v202, v152
	s_waitcnt vmcnt(0)
	s_barrier
	ds_read_b128 v[140:143], v174
	ds_read_b128 v[154:157], v174 offset:2048
	ds_read_b128 v[150:153], v182
	ds_read_b128 v[170:173], v174 offset:4096
	ds_read_b128 v[174:177], v174 offset:6144
	s_waitcnt lgkmcnt(2)
	v_mfma_f32_16x16x32_bf16 v[126:129], v[140:143], v[150:153], v[126:129]
	s_sext_i32_i8 s14, s20
	s_lshl_b32 s20, s14, 8
	s_ashr_i32 s21, s20, 31
	v_mfma_f32_16x16x32_bf16 v[122:125], v[154:157], v[150:153], v[122:125]
	s_waitcnt lgkmcnt(1)
	v_mfma_f32_16x16x32_bf16 v[118:121], v[170:173], v[150:153], v[118:121]
	s_waitcnt lgkmcnt(0)
	v_mfma_f32_16x16x32_bf16 v[114:117], v[174:177], v[150:153], v[114:117]
	ds_read_b128 v[150:153], v182 offset:2048
	s_waitcnt lgkmcnt(0)
	v_mfma_f32_16x16x32_bf16 v[110:113], v[140:143], v[150:153], v[110:113]
	v_mfma_f32_16x16x32_bf16 v[106:109], v[154:157], v[150:153], v[106:109]
	v_mfma_f32_16x16x32_bf16 v[102:105], v[170:173], v[150:153], v[102:105]
	v_mfma_f32_16x16x32_bf16 v[98:101], v[174:177], v[150:153], v[98:101]
	ds_read_b128 v[150:153], v182 offset:4096
	s_waitcnt lgkmcnt(0)
	v_mfma_f32_16x16x32_bf16 v[94:97], v[140:143], v[150:153], v[94:97]
	v_mfma_f32_16x16x32_bf16 v[90:93], v[154:157], v[150:153], v[90:93]
	v_mfma_f32_16x16x32_bf16 v[86:89], v[170:173], v[150:153], v[86:89]
	v_mfma_f32_16x16x32_bf16 v[82:85], v[174:177], v[150:153], v[82:85]
	ds_read_b128 v[150:153], v182 offset:6144
	s_waitcnt lgkmcnt(0)
	v_mfma_f32_16x16x32_bf16 v[78:81], v[140:143], v[150:153], v[78:81]
	v_mfma_f32_16x16x32_bf16 v[74:77], v[154:157], v[150:153], v[74:77]
	v_mfma_f32_16x16x32_bf16 v[70:73], v[170:173], v[150:153], v[70:73]
	v_mfma_f32_16x16x32_bf16 v[66:69], v[174:177], v[150:153], v[66:69]
	ds_read_b128 v[150:153], v182 offset:8192
	ds_read_b128 v[178:181], v182 offset:10240
	s_waitcnt lgkmcnt(1)
	v_mfma_f32_16x16x32_bf16 v[62:65], v[140:143], v[150:153], v[62:65]
	v_mfma_f32_16x16x32_bf16 v[58:61], v[154:157], v[150:153], v[58:61]
	v_mfma_f32_16x16x32_bf16 v[54:57], v[170:173], v[150:153], v[54:57]
	v_mfma_f32_16x16x32_bf16 v[50:53], v[174:177], v[150:153], v[50:53]
	ds_read_b128 v[150:153], v182 offset:12288
	s_waitcnt lgkmcnt(1)
	v_mfma_f32_16x16x32_bf16 v[46:49], v[140:143], v[178:181], v[46:49]
	v_mfma_f32_16x16x32_bf16 v[42:45], v[154:157], v[178:181], v[42:45]
	v_mfma_f32_16x16x32_bf16 v[34:37], v[170:173], v[178:181], v[34:37]
	v_mfma_f32_16x16x32_bf16 v[30:33], v[174:177], v[178:181], v[30:33]
	ds_read_b128 v[178:181], v182 offset:14336
	s_waitcnt lgkmcnt(1)
	v_mfma_f32_16x16x32_bf16 v[182:185], v[140:143], v[150:153], v[26:29]
	s_nop 2
	v_add_u32_e32 v29, v186, v149
	ds_read_b128 v[186:189], v29
	ds_read_b128 v[190:193], v29 offset:2048
	ds_read_b128 v[194:197], v29 offset:4096
	ds_read_b128 v[198:201], v29 offset:6144
	v_add_u32_e32 v29, v202, v149
	v_mfma_f32_16x16x32_bf16 v[22:25], v[154:157], v[150:153], v[22:25]
	v_and_b32_e32 v28, 0xc0, v144
	v_lshl_or_b32 v147, v147, 2, v28
	v_lshlrev_b32_e32 v28, 3, v146
	v_mfma_f32_16x16x32_bf16 v[18:21], v[170:173], v[150:153], v[18:21]
	v_lshl_add_u64 v[26:27], v[132:133], 0, s[12:13]
	v_lshl_add_u64 v[26:27], s[20:21], 1, v[26:27]
	s_mov_b32 s12, 0
	v_mfma_f32_16x16x32_bf16 v[14:17], v[174:177], v[150:153], v[14:17]
	ds_read_b128 v[150:153], v29
	ds_read_b128 v[202:205], v29 offset:2048
	ds_read_b128 v[206:209], v29 offset:4096
	ds_read_b128 v[210:213], v29 offset:6144
	s_waitcnt lgkmcnt(3)
	v_mfma_f32_16x16x32_bf16 v[126:129], v[186:189], v[150:153], v[126:129]
	v_mfma_f32_16x16x32_bf16 v[122:125], v[190:193], v[150:153], v[122:125]
	s_waitcnt lgkmcnt(1)
	v_mfma_f32_16x16x32_bf16 v[94:97], v[186:189], v[206:209], v[94:97]
	v_mfma_f32_16x16x32_bf16 v[10:13], v[140:143], v[178:181], v[10:13]
	ds_read_b128 v[140:143], v29 offset:8192
	ds_read_b128 v[214:217], v29 offset:10240
	ds_read_b128 v[218:221], v29 offset:12288
	ds_read_b128 v[222:225], v29 offset:14336
	v_lshlrev_b32_e32 v29, 9, v148
	v_and_or_b32 v146, v28, 8, v29
	v_mfma_f32_16x16x32_bf16 v[118:121], v[194:197], v[150:153], v[118:121]
	v_cvt_pk_bf16_f32 v28, v126, v127
	v_lshrrev_b32_e32 v126, 3, v147
	v_xor_b32_e32 v127, v126, v145
	v_mfma_f32_16x16x32_bf16 v[90:93], v[190:193], v[206:209], v[90:93]
	v_cvt_pk_bf16_f32 v29, v128, v129
	v_lshl_or_b32 v127, v127, 4, v146
	v_cvt_pk_bf16_f32 v122, v122, v123
	v_mfma_f32_16x16x32_bf16 v[114:117], v[198:201], v[150:153], v[114:117]
	v_cvt_pk_bf16_f32 v123, v124, v125
	v_bitop3_b32 v124, v126, v145, 2 bitop3:0x36
	v_cvt_pk_bf16_f32 v94, v94, v95
	v_mfma_f32_16x16x32_bf16 v[86:89], v[194:197], v[206:209], v[86:89]
	v_cvt_pk_bf16_f32 v95, v96, v97
	s_waitcnt lgkmcnt(0)
	s_barrier
	v_mfma_f32_16x16x32_bf16 v[110:113], v[186:189], v[202:205], v[110:113]
	v_lshl_add_u32 v124, v124, 4, v146
	v_cvt_pk_bf16_f32 v118, v118, v119
	v_mfma_f32_16x16x32_bf16 v[82:85], v[198:201], v[206:209], v[82:85]
	v_cvt_pk_bf16_f32 v119, v120, v121
	v_bitop3_b32 v120, v126, v145, 4 bitop3:0x36
	ds_write2st64_b64 v127, v[28:29], v[94:95] offset1:32
	v_mfma_f32_16x16x32_bf16 v[106:109], v[190:193], v[202:205], v[106:109]
	v_cvt_pk_bf16_f32 v28, v90, v91
	v_cvt_pk_bf16_f32 v29, v92, v93
	v_lshl_add_u32 v120, v120, 4, v146
	v_mfma_f32_16x16x32_bf16 v[78:81], v[186:189], v[210:213], v[78:81]
	v_cvt_pk_bf16_f32 v114, v114, v115
	v_cvt_pk_bf16_f32 v115, v116, v117
	v_bitop3_b32 v116, v126, v145, 6 bitop3:0x36
	v_mfma_f32_16x16x32_bf16 v[102:105], v[194:197], v[202:205], v[102:105]
	ds_write2st64_b64 v124, v[122:123], v[28:29] offset1:32
	v_cvt_pk_bf16_f32 v28, v86, v87
	v_cvt_pk_bf16_f32 v29, v88, v89
	v_mfma_f32_16x16x32_bf16 v[74:77], v[190:193], v[210:213], v[74:77]
	v_lshl_add_u32 v116, v116, 4, v146
	v_or_b32_e32 v117, 16, v145
	v_cvt_pk_bf16_f32 v110, v110, v111
	v_mfma_f32_16x16x32_bf16 v[2:5], v[170:173], v[178:181], v[2:5]
	v_cvt_pk_bf16_f32 v111, v112, v113
	v_bitop3_b32 v112, v126, v145, 16 bitop3:0x1e
	ds_write2st64_b64 v120, v[118:119], v[28:29] offset1:32
	v_mfma_f32_16x16x32_bf16 v[98:101], v[198:201], v[202:205], v[98:101]
	v_cvt_pk_bf16_f32 v28, v82, v83
	v_cvt_pk_bf16_f32 v29, v84, v85
	v_lshl_or_b32 v112, v112, 4, v146
	v_mfma_f32_16x16x32_bf16 v[70:73], v[194:197], v[210:213], v[70:73]
	v_cvt_pk_bf16_f32 v106, v106, v107
	v_cvt_pk_bf16_f32 v107, v108, v109
	v_bitop3_b32 v108, v126, v117, 2 bitop3:0x36
	v_mfma_f32_16x16x32_bf16 v[66:69], v[198:201], v[210:213], v[66:69]
	ds_write2st64_b64 v116, v[114:115], v[28:29] offset1:32
	v_cvt_pk_bf16_f32 v28, v78, v79
	v_cvt_pk_bf16_f32 v29, v80, v81
	v_lshl_add_u32 v108, v108, 4, v146
	v_cvt_pk_bf16_f32 v102, v102, v103
	v_cvt_pk_bf16_f32 v103, v104, v105
	v_bitop3_b32 v104, v126, v117, 4 bitop3:0x36
	ds_write2st64_b64 v112, v[110:111], v[28:29] offset0:16 offset1:48
	v_cvt_pk_bf16_f32 v28, v74, v75
	v_cvt_pk_bf16_f32 v29, v76, v77
	v_lshl_add_u32 v104, v104, 4, v146
	v_cvt_pk_bf16_f32 v98, v98, v99
	v_cvt_pk_bf16_f32 v99, v100, v101
	v_bitop3_b32 v100, v126, v117, 6 bitop3:0x36
	ds_write2st64_b64 v108, v[106:107], v[28:29] offset0:16 offset1:48
	v_cvt_pk_bf16_f32 v28, v70, v71
	v_cvt_pk_bf16_f32 v29, v72, v73
	v_mfma_f32_16x16x32_bf16 v[34:37], v[194:197], v[214:217], v[34:37]
	v_lshl_add_u32 v100, v100, 4, v146
	ds_write2st64_b64 v104, v[102:103], v[28:29] offset0:16 offset1:48
	v_cvt_pk_bf16_f32 v28, v66, v67
	v_mfma_f32_16x16x32_bf16 v[2:5], v[194:197], v[222:225], v[2:5]
	v_cvt_pk_bf16_f32 v29, v68, v69
	ds_write2st64_b64 v100, v[98:99], v[28:29] offset0:16 offset1:48
	s_nop 1
	v_cvt_pk_bf16_f32 v34, v34, v35
	v_mfma_f32_16x16x32_bf16 v[38:41], v[174:177], v[178:181], v[38:41]
	v_cvt_pk_bf16_f32 v35, v36, v37
	s_nop 0
	v_cvt_pk_bf16_f32 v2, v2, v3
	v_cvt_pk_bf16_f32 v3, v4, v5
	v_mfma_f32_16x16x32_bf16 v[6:9], v[154:157], v[178:181], v[6:9]
	ds_write2st64_b64 v104, v[34:35], v[2:3] offset0:80 offset1:112
	v_mfma_f32_16x16x32_bf16 v[28:31], v[198:201], v[214:217], v[30:33]
	v_mfma_f32_16x16x32_bf16 v[2:5], v[198:201], v[222:225], v[38:41]
	v_mfma_f32_16x16x32_bf16 v[62:65], v[186:189], v[140:143], v[62:65]
	s_nop 5
	v_cvt_pk_bf16_f32 v32, v28, v29
	v_cvt_pk_bf16_f32 v33, v30, v31
	v_cvt_pk_bf16_f32 v2, v2, v3
	v_mfma_f32_16x16x32_bf16 v[58:61], v[190:193], v[140:143], v[58:61]
	v_cvt_pk_bf16_f32 v3, v4, v5
	v_cvt_pk_bf16_f32 v62, v62, v63
	v_cvt_pk_bf16_f32 v63, v64, v65
	v_mfma_f32_16x16x32_bf16 v[54:57], v[194:197], v[140:143], v[54:57]
	ds_write2st64_b64 v100, v[32:33], v[2:3] offset0:80 offset1:112
	s_nop 2
	v_cvt_pk_bf16_f32 v58, v58, v59
	v_cvt_pk_bf16_f32 v59, v60, v61
	v_mfma_f32_16x16x32_bf16 v[50:53], v[198:201], v[140:143], v[50:53]
	v_and_b32_e32 v2, 0x1f0, v138
	v_cvt_pk_bf16_f32 v54, v54, v55
	v_cvt_pk_bf16_f32 v55, v56, v57
	v_mfma_f32_16x16x32_bf16 v[46:49], v[186:189], v[214:217], v[46:49]
	v_mfma_f32_16x16x32_bf16 v[42:45], v[190:193], v[214:217], v[42:45]
	s_nop 2
	v_cvt_pk_bf16_f32 v50, v50, v51
	v_cvt_pk_bf16_f32 v51, v52, v53
	s_nop 1
	v_cvt_pk_bf16_f32 v46, v46, v47
	v_mfma_f32_16x16x32_bf16 v[28:31], v[186:189], v[218:221], v[182:185]
	v_cvt_pk_bf16_f32 v47, v48, v49
	v_cvt_pk_bf16_f32 v42, v42, v43
	v_cvt_pk_bf16_f32 v43, v44, v45
	v_mfma_f32_16x16x32_bf16 v[22:25], v[190:193], v[218:221], v[22:25]
	v_mfma_f32_16x16x32_bf16 v[18:21], v[194:197], v[218:221], v[18:21]
	s_nop 2
	v_cvt_pk_bf16_f32 v28, v28, v29
	v_cvt_pk_bf16_f32 v29, v30, v31
	s_nop 1
	v_cvt_pk_bf16_f32 v22, v22, v23
	v_mfma_f32_16x16x32_bf16 v[14:17], v[198:201], v[218:221], v[14:17]
	v_cvt_pk_bf16_f32 v23, v24, v25
	v_cvt_pk_bf16_f32 v18, v18, v19
	v_cvt_pk_bf16_f32 v19, v20, v21
	v_mfma_f32_16x16x32_bf16 v[10:13], v[186:189], v[222:225], v[10:13]
	ds_write2st64_b64 v127, v[62:63], v[28:29] offset0:64 offset1:96
	s_nop 2
	v_cvt_pk_bf16_f32 v14, v14, v15
	v_cvt_pk_bf16_f32 v15, v16, v17
	v_mfma_f32_16x16x32_bf16 v[6:9], v[190:193], v[222:225], v[6:9]
	ds_write2st64_b64 v124, v[58:59], v[22:23] offset0:64 offset1:96
	v_cvt_pk_bf16_f32 v10, v10, v11
	v_cvt_pk_bf16_f32 v11, v12, v13
	ds_write2st64_b64 v120, v[54:55], v[18:19] offset0:64 offset1:96
	ds_write2st64_b64 v116, v[50:51], v[14:15] offset0:64 offset1:96
	s_nop 2
	v_cvt_pk_bf16_f32 v6, v6, v7
	v_cvt_pk_bf16_f32 v7, v8, v9
	ds_write2st64_b64 v112, v[46:47], v[10:11] offset0:80 offset1:112
	ds_write2st64_b64 v108, v[42:43], v[6:7] offset0:80 offset1:112
	s_waitcnt lgkmcnt(0)
	s_barrier

.LBB0_1466:
	s_and_b32 s48, s21, 0x10000
	s_xor_b32 s49, s48, 0x10000
	v_add_u32_e32 v216, s49, v140
	v_add_u32_e32 v217, s49, v153
	s_waitcnt vmcnt(0) lgkmcnt(0)
	s_barrier
	v_readfirstlane_b32 s50, v142
	v_readfirstlane_b32 s51, v143
	v_readfirstlane_b32 s58, v144
	v_readfirstlane_b32 s59, v145
	v_or_b32_e32 v248, s48, v155
	v_add_u32_e32 v249, s48, v152
	v_add_u32_e32 v244, v248, v154
	v_add_u32_e32 v245, v249, v154
	ds_read_b128 v[162:165], v244 offset:32768
	ds_read_b128 v[166:169], v244 offset:34816
	ds_read_b128 v[170:173], v244 offset:36864
	ds_read_b128 v[174:177], v244 offset:38912
	ds_read_b128 v[228:231], v245
	ds_read_b128 v[232:235], v245 offset:2048
	ds_read_b128 v[236:239], v245 offset:4096
	ds_read_b128 v[240:243], v245 offset:6144
	v_readfirstlane_b32 s40, v216
	v_readfirstlane_b32 s44, v217
	v_subrev_u32_e32 v218, s50, v142
	v_subrev_u32_e32 v219, s58, v144
	v_add_u32_e32 v246, v248, v151
	v_add_u32_e32 v247, v249, v151
	s_mov_b32 m0, s40
	s_add_u32 s52, s50, s4
	s_addc_u32 s53, s51, s5
	global_load_lds_dwordx4 v218, s[50:51]
	s_mov_b32 m0, s44
	s_add_u32 s60, s58, s4
	s_addc_u32 s61, s59, s5
	global_load_lds_dwordx4 v219, s[58:59]
	s_add_i32 s41, s40, 0x2000
	s_add_i32 s45, s44, 0x2000
	s_add_i32 s42, s40, 0x4000
	s_add_i32 s46, s44, 0x4000
	s_add_i32 s43, s40, 0x6000
	s_add_i32 s47, s44, 0x6000
	s_add_i32 s21, s21, 0x10000
	s_waitcnt lgkmcnt(3)
	v_mfma_f32_16x16x32_bf16 v[126:129], v[162:165], v[228:231], v[126:129]
	s_add_u32 s54, s50, s6
	s_addc_u32 s55, s51, s7
	v_mfma_f32_16x16x32_bf16 v[122:125], v[166:169], v[228:231], v[122:125]
	s_add_u32 s62, s58, s6
	s_addc_u32 s63, s59, s7
	v_mfma_f32_16x16x32_bf16 v[118:121], v[170:173], v[228:231], v[118:121]
	s_add_u32 s56, s50, s8
	s_addc_u32 s57, s51, s9
	v_mfma_f32_16x16x32_bf16 v[114:117], v[174:177], v[228:231], v[114:117]
	s_add_u32 s64, s58, s8
	s_addc_u32 s65, s59, s9
	s_waitcnt lgkmcnt(2)
	v_mfma_f32_16x16x32_bf16 v[110:113], v[162:165], v[232:235], v[110:113]
	v_mfma_f32_16x16x32_bf16 v[106:109], v[166:169], v[232:235], v[106:109]
	v_mfma_f32_16x16x32_bf16 v[102:105], v[170:173], v[232:235], v[102:105]
	v_mfma_f32_16x16x32_bf16 v[98:101], v[174:177], v[232:235], v[98:101]
	s_waitcnt lgkmcnt(1)
	v_mfma_f32_16x16x32_bf16 v[94:97], v[162:165], v[236:239], v[94:97]
	ds_read_b128 v[228:231], v245 offset:8192
	v_mfma_f32_16x16x32_bf16 v[90:93], v[166:169], v[236:239], v[90:93]
	ds_read_b128 v[232:235], v245 offset:10240
	v_mfma_f32_16x16x32_bf16 v[86:89], v[170:173], v[236:239], v[86:89]
	s_mov_b32 m0, s41
	v_mfma_f32_16x16x32_bf16 v[82:85], v[174:177], v[236:239], v[82:85]
	global_load_lds_dwordx4 v218, s[52:53]
	s_waitcnt lgkmcnt(2)
	v_mfma_f32_16x16x32_bf16 v[78:81], v[162:165], v[240:243], v[78:81]
	s_mov_b32 m0, s45
	v_mfma_f32_16x16x32_bf16 v[74:77], v[166:169], v[240:243], v[74:77]
	global_load_lds_dwordx4 v219, s[60:61]
	v_mfma_f32_16x16x32_bf16 v[70:73], v[170:173], v[240:243], v[70:73]
	v_mfma_f32_16x16x32_bf16 v[66:69], v[174:177], v[240:243], v[66:69]
	s_waitcnt lgkmcnt(1)
	v_mfma_f32_16x16x32_bf16 v[62:65], v[162:165], v[228:231], v[62:65]
	ds_read_b128 v[236:239], v245 offset:12288
	v_mfma_f32_16x16x32_bf16 v[58:61], v[166:169], v[228:231], v[58:61]
	ds_read_b128 v[240:243], v245 offset:14336
	v_mfma_f32_16x16x32_bf16 v[54:57], v[170:173], v[228:231], v[54:57]
	s_mov_b32 m0, s42
	v_mfma_f32_16x16x32_bf16 v[50:53], v[174:177], v[228:231], v[50:53]
	global_load_lds_dwordx4 v218, s[54:55]
	s_waitcnt lgkmcnt(2)
	v_mfma_f32_16x16x32_bf16 v[46:49], v[162:165], v[232:235], v[46:49]
	s_mov_b32 m0, s46
	v_mfma_f32_16x16x32_bf16 v[42:45], v[166:169], v[232:235], v[42:45]
	global_load_lds_dwordx4 v219, s[62:63]
	v_mfma_f32_16x16x32_bf16 v[34:37], v[170:173], v[232:235], v[34:37]
	v_mfma_f32_16x16x32_bf16 v[30:33], v[174:177], v[232:235], v[30:33]
	s_waitcnt lgkmcnt(1)
	v_mfma_f32_16x16x32_bf16 v[26:29], v[162:165], v[236:239], v[26:29]
	ds_read_b128 v[178:181], v246 offset:32768
	v_mfma_f32_16x16x32_bf16 v[22:25], v[166:169], v[236:239], v[22:25]
	ds_read_b128 v[182:185], v246 offset:34816
	v_mfma_f32_16x16x32_bf16 v[18:21], v[170:173], v[236:239], v[18:21]
	ds_read_b128 v[220:223], v246 offset:36864
	v_mfma_f32_16x16x32_bf16 v[14:17], v[174:177], v[236:239], v[14:17]
	ds_read_b128 v[224:227], v246 offset:38912
	s_waitcnt lgkmcnt(4)
	v_mfma_f32_16x16x32_bf16 v[10:13], v[162:165], v[240:243], v[10:13]
	ds_read_b128 v[228:231], v247
	v_mfma_f32_16x16x32_bf16 v[6:9], v[166:169], v[240:243], v[6:9]
	ds_read_b128 v[232:235], v247 offset:2048
	v_mfma_f32_16x16x32_bf16 v[2:5], v[170:173], v[240:243], v[2:5]
	s_mov_b32 m0, s43
	v_mfma_f32_16x16x32_bf16 v[38:41], v[174:177], v[240:243], v[38:41]
	global_load_lds_dwordx4 v218, s[56:57]
	s_mov_b32 m0, s47
	v_lshl_add_u64 v[142:143], v[142:143], 0, s[10:11]
	global_load_lds_dwordx4 v219, s[64:65]
	v_lshl_add_u64 v[144:145], v[144:145], 0, s[10:11]
	s_waitcnt lgkmcnt(1)
	v_mfma_f32_16x16x32_bf16 v[126:129], v[178:181], v[228:231], v[126:129]
	ds_read_b128 v[236:239], v247 offset:4096
	v_mfma_f32_16x16x32_bf16 v[122:125], v[182:185], v[228:231], v[122:125]
	ds_read_b128 v[240:243], v247 offset:6144
	v_mfma_f32_16x16x32_bf16 v[118:121], v[220:223], v[228:231], v[118:121]
	v_mfma_f32_16x16x32_bf16 v[114:117], v[224:227], v[228:231], v[114:117]
	s_waitcnt lgkmcnt(2)
	v_mfma_f32_16x16x32_bf16 v[110:113], v[178:181], v[232:235], v[110:113]
	v_mfma_f32_16x16x32_bf16 v[106:109], v[182:185], v[232:235], v[106:109]
	v_mfma_f32_16x16x32_bf16 v[102:105], v[220:223], v[232:235], v[102:105]
	v_mfma_f32_16x16x32_bf16 v[98:101], v[224:227], v[232:235], v[98:101]
	s_waitcnt lgkmcnt(1)
	v_mfma_f32_16x16x32_bf16 v[94:97], v[178:181], v[236:239], v[94:97]
	ds_read_b128 v[228:231], v247 offset:8192
	v_mfma_f32_16x16x32_bf16 v[90:93], v[182:185], v[236:239], v[90:93]
	ds_read_b128 v[232:235], v247 offset:10240
	v_mfma_f32_16x16x32_bf16 v[86:89], v[220:223], v[236:239], v[86:89]
	v_mfma_f32_16x16x32_bf16 v[82:85], v[224:227], v[236:239], v[82:85]
	s_waitcnt lgkmcnt(2)
	v_mfma_f32_16x16x32_bf16 v[78:81], v[178:181], v[240:243], v[78:81]
	v_mfma_f32_16x16x32_bf16 v[74:77], v[182:185], v[240:243], v[74:77]
	v_mfma_f32_16x16x32_bf16 v[70:73], v[220:223], v[240:243], v[70:73]
	v_mfma_f32_16x16x32_bf16 v[66:69], v[224:227], v[240:243], v[66:69]
	s_waitcnt lgkmcnt(1)
	v_mfma_f32_16x16x32_bf16 v[62:65], v[178:181], v[228:231], v[62:65]
	ds_read_b128 v[236:239], v247 offset:12288
	v_mfma_f32_16x16x32_bf16 v[58:61], v[182:185], v[228:231], v[58:61]
	ds_read_b128 v[240:243], v247 offset:14336
	v_mfma_f32_16x16x32_bf16 v[54:57], v[220:223], v[228:231], v[54:57]
	v_mfma_f32_16x16x32_bf16 v[50:53], v[224:227], v[228:231], v[50:53]
	s_waitcnt lgkmcnt(2)
	v_mfma_f32_16x16x32_bf16 v[46:49], v[178:181], v[232:235], v[46:49]
	v_mfma_f32_16x16x32_bf16 v[42:45], v[182:185], v[232:235], v[42:45]
	v_mfma_f32_16x16x32_bf16 v[34:37], v[220:223], v[232:235], v[34:37]
	v_mfma_f32_16x16x32_bf16 v[30:33], v[224:227], v[232:235], v[30:33]
	s_waitcnt lgkmcnt(1)
	v_mfma_f32_16x16x32_bf16 v[26:29], v[178:181], v[236:239], v[26:29]
	v_mfma_f32_16x16x32_bf16 v[22:25], v[182:185], v[236:239], v[22:25]
	v_mfma_f32_16x16x32_bf16 v[18:21], v[220:223], v[236:239], v[18:21]
	v_mfma_f32_16x16x32_bf16 v[14:17], v[224:227], v[236:239], v[14:17]
	s_waitcnt lgkmcnt(0)
	v_mfma_f32_16x16x32_bf16 v[10:13], v[178:181], v[240:243], v[10:13]
	v_mfma_f32_16x16x32_bf16 v[6:9], v[182:185], v[240:243], v[6:9]
	v_mfma_f32_16x16x32_bf16 v[2:5], v[220:223], v[240:243], v[2:5]
	v_mfma_f32_16x16x32_bf16 v[38:41], v[224:227], v[240:243], v[38:41]
	s_cmp_eq_u32 s21, 0x1f0000
	s_cbranch_scc0 .LBB0_1466
	v_or_b32_e32 v184, 0x18000, v155
	v_add_u32_e32 v156, v184, v154
	s_waitcnt vmcnt(0)
	s_barrier
	ds_read_b128 v[142:145], v156
	ds_read_b128 v[162:165], v156 offset:2048
	ds_read_b128 v[166:169], v156 offset:4096
	ds_read_b128 v[170:173], v156 offset:6144
	v_add_u32_e32 v198, 0x10000, v152
	v_add_u32_e32 v178, v198, v154
	ds_read_b128 v[152:155], v178
	s_waitcnt lgkmcnt(0)
	v_mfma_f32_16x16x32_bf16 v[126:129], v[142:145], v[152:155], v[126:129]
	s_sext_i32_i8 s14, s20
	s_lshl_b32 s20, s14, 8
	s_ashr_i32 s21, s20, 31
	v_mfma_f32_16x16x32_bf16 v[122:125], v[162:165], v[152:155], v[122:125]
	v_lshl_add_u64 v[156:157], v[134:135], 0, s[12:13]
	v_lshl_add_u64 v[182:183], v[130:131], 0, s[12:13]
	s_lshl_b64 s[12:13], s[20:21], 1
	v_mfma_f32_16x16x32_bf16 v[118:121], v[166:169], v[152:155], v[118:121]
	v_lshlrev_b32_e32 v148, 3, v148
	v_lshlrev_b32_e32 v150, 9, v150
	v_and_or_b32 v148, v148, 8, v150
	v_mfma_f32_16x16x32_bf16 v[114:117], v[170:173], v[152:155], v[114:117]
	ds_read_b128 v[152:155], v178 offset:2048
	s_waitcnt lgkmcnt(0)
	v_mfma_f32_16x16x32_bf16 v[110:113], v[142:145], v[152:155], v[110:113]
	v_mfma_f32_16x16x32_bf16 v[106:109], v[162:165], v[152:155], v[106:109]
	v_mfma_f32_16x16x32_bf16 v[102:105], v[166:169], v[152:155], v[102:105]
	v_mfma_f32_16x16x32_bf16 v[98:101], v[170:173], v[152:155], v[98:101]
	ds_read_b128 v[152:155], v178 offset:4096
	s_waitcnt lgkmcnt(0)
	v_mfma_f32_16x16x32_bf16 v[94:97], v[142:145], v[152:155], v[94:97]
	v_mfma_f32_16x16x32_bf16 v[90:93], v[162:165], v[152:155], v[90:93]
	v_mfma_f32_16x16x32_bf16 v[86:89], v[166:169], v[152:155], v[86:89]
	v_mfma_f32_16x16x32_bf16 v[82:85], v[170:173], v[152:155], v[82:85]
	ds_read_b128 v[152:155], v178 offset:6144
	s_waitcnt lgkmcnt(0)
	v_mfma_f32_16x16x32_bf16 v[78:81], v[142:145], v[152:155], v[78:81]
	v_mfma_f32_16x16x32_bf16 v[74:77], v[162:165], v[152:155], v[74:77]
	v_mfma_f32_16x16x32_bf16 v[70:73], v[166:169], v[152:155], v[70:73]
	v_mfma_f32_16x16x32_bf16 v[66:69], v[170:173], v[152:155], v[66:69]
	ds_read_b128 v[152:155], v178 offset:8192
	ds_read_b128 v[174:177], v178 offset:10240
	s_waitcnt lgkmcnt(1)
	v_mfma_f32_16x16x32_bf16 v[62:65], v[142:145], v[152:155], v[62:65]
	v_mfma_f32_16x16x32_bf16 v[58:61], v[162:165], v[152:155], v[58:61]
	v_mfma_f32_16x16x32_bf16 v[54:57], v[166:169], v[152:155], v[54:57]
	v_mfma_f32_16x16x32_bf16 v[50:53], v[170:173], v[152:155], v[50:53]
	ds_read_b128 v[152:155], v178 offset:12288
	s_waitcnt lgkmcnt(1)
	v_mfma_f32_16x16x32_bf16 v[46:49], v[142:145], v[174:177], v[46:49]
	v_mfma_f32_16x16x32_bf16 v[42:45], v[162:165], v[174:177], v[42:45]
	v_mfma_f32_16x16x32_bf16 v[34:37], v[166:169], v[174:177], v[34:37]
	v_mfma_f32_16x16x32_bf16 v[30:33], v[170:173], v[174:177], v[30:33]
	ds_read_b128 v[174:177], v178 offset:14336
	s_waitcnt lgkmcnt(1)
	v_mfma_f32_16x16x32_bf16 v[178:181], v[142:145], v[152:155], v[26:29]
	s_nop 2
	v_lshl_add_u64 v[28:29], v[156:157], 0, s[12:13]
	v_add_u32_e32 v157, v184, v151
	v_lshl_add_u64 v[26:27], v[182:183], 0, s[12:13]
	ds_read_b128 v[182:185], v157
	ds_read_b128 v[186:189], v157 offset:2048
	ds_read_b128 v[190:193], v157 offset:4096
	ds_read_b128 v[194:197], v157 offset:6144
	v_add_u32_e32 v151, v198, v151
	v_mfma_f32_16x16x32_bf16 v[22:25], v[162:165], v[152:155], v[22:25]
	v_and_b32_e32 v156, 0xc0, v146
	v_lshl_or_b32 v149, v149, 2, v156
	s_mov_b32 s12, 0
	v_mfma_f32_16x16x32_bf16 v[18:21], v[166:169], v[152:155], v[18:21]
	v_mfma_f32_16x16x32_bf16 v[14:17], v[170:173], v[152:155], v[14:17]
	ds_read_b128 v[152:155], v151
	ds_read_b128 v[198:201], v151 offset:2048
	ds_read_b128 v[202:205], v151 offset:4096
	ds_read_b128 v[206:209], v151 offset:6144
	s_waitcnt lgkmcnt(8)
	v_mfma_f32_16x16x32_bf16 v[10:13], v[142:145], v[174:177], v[10:13]
	ds_read_b128 v[142:145], v151 offset:8192
	ds_read_b128 v[210:213], v151 offset:10240
	ds_read_b128 v[214:217], v151 offset:12288
	ds_read_b128 v[218:221], v151 offset:14336
	s_waitcnt lgkmcnt(0)
	s_barrier
	v_mfma_f32_16x16x32_bf16 v[2:5], v[166:169], v[174:177], v[2:5]
	v_mfma_f32_16x16x32_bf16 v[126:129], v[182:185], v[152:155], v[126:129]
	v_mfma_f32_16x16x32_bf16 v[114:117], v[194:197], v[152:155], v[114:117]
	v_mfma_f32_16x16x32_bf16 v[102:105], v[190:193], v[198:201], v[102:105]
	s_nop 5
	v_cvt_pk_bf16_f32 v126, v126, v127
	v_cvt_pk_bf16_f32 v127, v128, v129
	v_lshrrev_b32_e32 v128, 3, v149
	v_mfma_f32_16x16x32_bf16 v[34:37], v[190:193], v[210:213], v[34:37]
	v_cvt_pk_bf16_f32 v114, v114, v115
	v_cvt_pk_bf16_f32 v115, v116, v117
	v_or_b32_e32 v117, 16, v147
	v_mfma_f32_16x16x32_bf16 v[2:5], v[190:193], v[218:221], v[2:5]
	v_cvt_pk_bf16_f32 v102, v102, v103
	v_cvt_pk_bf16_f32 v103, v104, v105
	v_bitop3_b32 v104, v128, v117, 4 bitop3:0x36
	v_mfma_f32_16x16x32_bf16 v[38:41], v[170:173], v[174:177], v[38:41]
	v_lshl_add_u32 v104, v104, 4, v148
	v_cvt_pk_bf16_f32 v34, v34, v35
	v_cvt_pk_bf16_f32 v35, v36, v37
	v_mfma_f32_16x16x32_bf16 v[6:9], v[162:165], v[174:177], v[6:9]
	v_cvt_pk_bf16_f32 v2, v2, v3
	v_cvt_pk_bf16_f32 v3, v4, v5
	ds_write2st64_b64 v104, v[34:35], v[2:3] offset0:80 offset1:112
	v_mfma_f32_16x16x32_bf16 v[30:33], v[194:197], v[210:213], v[30:33]
	v_xor_b32_e32 v129, v128, v147
	v_bitop3_b32 v116, v128, v147, 6 bitop3:0x36
	v_lshl_or_b32 v129, v129, 4, v148
	v_mfma_f32_16x16x32_bf16 v[98:101], v[194:197], v[198:201], v[98:101]
	v_lshl_add_u32 v116, v116, 4, v148
	s_nop 2
	v_cvt_pk_bf16_f32 v36, v30, v31
	v_cvt_pk_bf16_f32 v37, v32, v33
	v_mfma_f32_16x16x32_bf16 v[122:125], v[186:189], v[152:155], v[122:125]
	v_mfma_f32_16x16x32_bf16 v[118:121], v[190:193], v[152:155], v[118:121]
	v_cvt_pk_bf16_f32 v98, v98, v99
	v_cvt_pk_bf16_f32 v99, v100, v101
	v_bitop3_b32 v100, v128, v117, 6 bitop3:0x36
	v_mfma_f32_16x16x32_bf16 v[110:113], v[182:185], v[198:201], v[110:113]
	s_nop 2
	v_cvt_pk_bf16_f32 v122, v122, v123
	v_cvt_pk_bf16_f32 v123, v124, v125
	v_bitop3_b32 v124, v128, v147, 2 bitop3:0x36
	v_mfma_f32_16x16x32_bf16 v[106:109], v[186:189], v[198:201], v[106:109]
	v_cvt_pk_bf16_f32 v118, v118, v119
	v_cvt_pk_bf16_f32 v119, v120, v121
	v_bitop3_b32 v120, v128, v147, 4 bitop3:0x36
	v_mfma_f32_16x16x32_bf16 v[2:5], v[194:197], v[218:221], v[38:41]
	v_cvt_pk_bf16_f32 v110, v110, v111
	v_cvt_pk_bf16_f32 v111, v112, v113
	v_bitop3_b32 v112, v128, v147, 16 bitop3:0x1e
	v_mfma_f32_16x16x32_bf16 v[94:97], v[182:185], v[202:205], v[94:97]
	v_cvt_pk_bf16_f32 v106, v106, v107
	v_cvt_pk_bf16_f32 v107, v108, v109
	v_bitop3_b32 v108, v128, v117, 2 bitop3:0x36
	v_mfma_f32_16x16x32_bf16 v[90:93], v[186:189], v[202:205], v[90:93]
	v_lshl_add_u32 v100, v100, 4, v148
	v_cvt_pk_bf16_f32 v2, v2, v3
	v_cvt_pk_bf16_f32 v3, v4, v5
	v_mfma_f32_16x16x32_bf16 v[86:89], v[190:193], v[202:205], v[86:89]
	v_lshl_add_u32 v124, v124, 4, v148
	v_lshl_add_u32 v120, v120, 4, v148
	v_lshl_or_b32 v112, v112, 4, v148
	v_mfma_f32_16x16x32_bf16 v[82:85], v[194:197], v[202:205], v[82:85]
	v_lshl_add_u32 v108, v108, 4, v148
	v_cvt_pk_bf16_f32 v94, v94, v95
	v_cvt_pk_bf16_f32 v95, v96, v97
	v_mfma_f32_16x16x32_bf16 v[78:81], v[182:185], v[206:209], v[78:81]
	v_cvt_pk_bf16_f32 v90, v90, v91
	v_cvt_pk_bf16_f32 v91, v92, v93
	v_cvt_pk_bf16_f32 v86, v86, v87
	v_mfma_f32_16x16x32_bf16 v[74:77], v[186:189], v[206:209], v[74:77]
	v_cvt_pk_bf16_f32 v87, v88, v89
	v_cvt_pk_bf16_f32 v82, v82, v83
	v_cvt_pk_bf16_f32 v83, v84, v85
	v_mfma_f32_16x16x32_bf16 v[70:73], v[190:193], v[206:209], v[70:73]
	v_cvt_pk_bf16_f32 v78, v78, v79
	v_cvt_pk_bf16_f32 v79, v80, v81
	s_nop 1
	v_cvt_pk_bf16_f32 v74, v74, v75
	v_mfma_f32_16x16x32_bf16 v[66:69], v[194:197], v[206:209], v[66:69]
	v_cvt_pk_bf16_f32 v75, v76, v77
	s_nop 0
	v_cvt_pk_bf16_f32 v70, v70, v71
	v_cvt_pk_bf16_f32 v71, v72, v73
	v_mfma_f32_16x16x32_bf16 v[62:65], v[182:185], v[142:145], v[62:65]
	ds_write2st64_b64 v100, v[36:37], v[2:3] offset0:80 offset1:112
	s_nop 1
	v_cvt_pk_bf16_f32 v66, v66, v67
	v_cvt_pk_bf16_f32 v67, v68, v69
	v_mfma_f32_16x16x32_bf16 v[58:61], v[186:189], v[142:145], v[58:61]
	v_and_b32_e32 v2, 0x1f0, v140
	s_nop 0
	v_cvt_pk_bf16_f32 v62, v62, v63
	v_cvt_pk_bf16_f32 v63, v64, v65
	v_mfma_f32_16x16x32_bf16 v[54:57], v[190:193], v[142:145], v[54:57]
	ds_write2st64_b64 v129, v[126:127], v[94:95] offset1:32
	s_nop 1
	v_cvt_pk_bf16_f32 v58, v58, v59
	v_cvt_pk_bf16_f32 v59, v60, v61
	v_mfma_f32_16x16x32_bf16 v[50:53], v[194:197], v[142:145], v[50:53]
	ds_write2st64_b64 v124, v[122:123], v[90:91] offset1:32
	s_nop 0
	v_cvt_pk_bf16_f32 v54, v54, v55
	v_cvt_pk_bf16_f32 v55, v56, v57
	v_mfma_f32_16x16x32_bf16 v[46:49], v[182:185], v[210:213], v[46:49]
	ds_write2st64_b64 v120, v[118:119], v[86:87] offset1:32
	s_nop 1
	v_cvt_pk_bf16_f32 v50, v50, v51
	v_cvt_pk_bf16_f32 v51, v52, v53
	v_mfma_f32_16x16x32_bf16 v[42:45], v[186:189], v[210:213], v[42:45]
	ds_write2st64_b64 v116, v[114:115], v[82:83] offset1:32
	s_nop 0
	v_cvt_pk_bf16_f32 v46, v46, v47
	v_cvt_pk_bf16_f32 v47, v48, v49
	v_mfma_f32_16x16x32_bf16 v[30:33], v[182:185], v[214:217], v[178:181]
	ds_write2st64_b64 v112, v[110:111], v[78:79] offset0:16 offset1:48
	s_nop 1
	v_cvt_pk_bf16_f32 v42, v42, v43
	v_cvt_pk_bf16_f32 v43, v44, v45
	v_mfma_f32_16x16x32_bf16 v[22:25], v[186:189], v[214:217], v[22:25]
	ds_write2st64_b64 v108, v[106:107], v[74:75] offset0:16 offset1:48
	s_nop 0
	v_cvt_pk_bf16_f32 v30, v30, v31
	v_cvt_pk_bf16_f32 v31, v32, v33
	v_mfma_f32_16x16x32_bf16 v[18:21], v[190:193], v[214:217], v[18:21]
	ds_write2st64_b64 v104, v[102:103], v[70:71] offset0:16 offset1:48
	s_nop 1
	v_cvt_pk_bf16_f32 v22, v22, v23
	v_cvt_pk_bf16_f32 v23, v24, v25
	v_mfma_f32_16x16x32_bf16 v[14:17], v[194:197], v[214:217], v[14:17]
	ds_write2st64_b64 v100, v[98:99], v[66:67] offset0:16 offset1:48
	s_nop 0
	v_cvt_pk_bf16_f32 v18, v18, v19
	v_cvt_pk_bf16_f32 v19, v20, v21
	v_mfma_f32_16x16x32_bf16 v[10:13], v[182:185], v[218:221], v[10:13]
	ds_write2st64_b64 v129, v[62:63], v[30:31] offset0:64 offset1:96
	s_nop 1
	v_cvt_pk_bf16_f32 v14, v14, v15
	v_cvt_pk_bf16_f32 v15, v16, v17
	v_mfma_f32_16x16x32_bf16 v[6:9], v[186:189], v[218:221], v[6:9]
	ds_write2st64_b64 v124, v[58:59], v[22:23] offset0:64 offset1:96
	s_nop 0
	v_cvt_pk_bf16_f32 v10, v10, v11
	v_cvt_pk_bf16_f32 v11, v12, v13
	ds_write2st64_b64 v120, v[54:55], v[18:19] offset0:64 offset1:96
	ds_write2st64_b64 v116, v[50:51], v[14:15] offset0:64 offset1:96
	s_nop 1
	v_cvt_pk_bf16_f32 v6, v6, v7
	v_cvt_pk_bf16_f32 v7, v8, v9
	ds_write2st64_b64 v112, v[46:47], v[10:11] offset0:80 offset1:112
	ds_write2st64_b64 v108, v[42:43], v[6:7] offset0:80 offset1:112
	s_waitcnt lgkmcnt(0)
	s_barrier
